# all late de-serialisation edits combined (FINAL-norm loop fully batched incl. merged rms batches, RoPE section loads hoisted) plus three provably redundant back-to-back s_barrier removed
# speedup vs baseline: 1.0011x; 1.0002x over previous
; DI int tidx() { int t = __builtin_amdgcn_workitem_id_x(); asm volatile("" : "+v"(t)); return t; }
; DI float bflo(unsigned u) { return __uint_as_float(u << 16); }
; DI float bfhi(unsigned u) { return __uint_as_float(u & 0xffff0000u); }
; DI float rstd16(const float* ssq, int m) {
;   float s = 0.f;
; #pragma unroll
;   for (int c = 0; c < 16; ++c) s += ssq[(size_t)c * TP + m];
;   return rsqrtf(s * (1.f / 1024.f) + RMS_EPS);
; }
; DI void final_rows(CP p, int item) {
;   const int lane = tidx() & 63, wv = tidx() >> 6;
;   const int orow = item * 8 + wv;
;   int r;
;   if (orow < 16384) { int s = orow >> 13; r = s * LPR + 16 + (orow & 8191); }
;   else { int x = orow - 16384; int s = x >> 11; r = 2 * LPR + s * LSM + 16 + (x & 2047); }
;   const float rs = rstd16(p.ssq, r);
;   const u16* src = p.hb + (size_t)r * 1024 + lane * 16;
;   uint4 a = *(const uint4*)src, b = *(const uint4*)(src + 8);
;   unsigned w[8] = {a.x, a.y, a.z, a.w, b.x, b.y, b.z, b.w};
;   float* dst = p.out + (size_t)orow * 1024 + lane * 16;
;   const float* gn = p.final_norm + lane * 16;
; #pragma unroll
;   for (int i = 0; i < 4; ++i) {
;     float4 o;
;     o.x = bflo(w[2 * i]) * rs * gn[4 * i]; o.y = bfhi(w[2 * i]) * rs * gn[4 * i + 1];
;     o.z = bflo(w[2 * i + 1]) * rs * gn[4 * i + 2]; o.w = bfhi(w[2 * i + 1]) * rs * gn[4 * i + 3];
;     *(float4*)(dst + 4 * i) = o;
;   }
; }
.LBB0_14:
	s_or_b64 exec, exec, s[8:9]
	s_load_dwordx2 s[8:9], s[0:1], 0x128
	v_and_b32_e32 v5, v5, v2
	v_add3_u32 v4, v5, v4, v3
	v_ashrrev_i32_e32 v5, 31, v4
	v_lshlrev_b32_e32 v0, 4, v0
	s_waitcnt lgkmcnt(0)
	v_lshl_add_u64 v[6:7], v[4:5], 2, s[8:9]
	s_waitcnt vmcnt(2)
	v_add_co_u32_e32 v8, vcc, 0x20000, v6
	v_lshlrev_b64 v[4:5], 11, v[4:5]
	s_nop 0
	v_addc_co_u32_e32 v9, vcc, 0, v7, vcc
	v_add_co_u32_e32 v10, vcc, 0x40000, v6
	s_add_i32 s14, s14, s94
	s_nop 0
	v_addc_co_u32_e32 v11, vcc, 0, v7, vcc
	v_add_co_u32_e32 v12, vcc, 0x60000, v6
	s_add_i32 s11, s11, s10
	s_nop 0
	v_addc_co_u32_e32 v13, vcc, 0, v7, vcc
	v_add_co_u32_e32 v14, vcc, 0x81000, v6
	s_cmpk_gt_i32 s14, 0xfff
	s_nop 0
	v_addc_co_u32_e32 v15, vcc, 0, v7, vcc
	s_waitcnt vmcnt(1)
	v_add_co_u32_e32 v16, vcc, 0xa1000, v6
	s_nop 1
	v_addc_co_u32_e32 v17, vcc, 0, v7, vcc
	v_add_co_u32_e32 v18, vcc, 0xc1000, v6
	s_nop 1
	v_addc_co_u32_e32 v19, vcc, 0, v7, vcc
	s_waitcnt vmcnt(0)
	v_add_co_u32_e32 v20, vcc, 0xe1000, v6
	s_nop 1
	v_addc_co_u32_e32 v21, vcc, 0, v7, vcc
	global_load_dword v3, v[6:7], off
	global_load_dword v22, v[8:9], off offset:1024
	global_load_dword v23, v[10:11], off offset:2048
	global_load_dword v24, v[12:13], off offset:3072
	global_load_dword v25, v[14:15], off
	global_load_dword v26, v[16:17], off offset:1024
	global_load_dword v27, v[18:19], off offset:2048
	global_load_dword v28, v[20:21], off offset:3072
	v_add_co_u32_e32 v216, vcc, 0x102000, v6
	s_nop 1
	v_addc_co_u32_e32 v217, vcc, 0, v7, vcc
	v_add_co_u32_e32 v218, vcc, 0x122000, v6
	s_nop 1
	v_addc_co_u32_e32 v219, vcc, 0, v7, vcc
	v_add_co_u32_e32 v220, vcc, 0x142000, v6
	s_nop 1
	v_addc_co_u32_e32 v221, vcc, 0, v7, vcc
	v_add_co_u32_e32 v222, vcc, 0x162000, v6
	s_nop 1
	v_addc_co_u32_e32 v223, vcc, 0, v7, vcc
	v_add_co_u32_e32 v224, vcc, 0x183000, v6
	s_nop 1
	v_addc_co_u32_e32 v225, vcc, 0, v7, vcc
	v_add_co_u32_e32 v226, vcc, 0x1a3000, v6
	s_nop 1
	v_addc_co_u32_e32 v227, vcc, 0, v7, vcc
	v_add_co_u32_e32 v228, vcc, 0x1c3000, v6
	s_nop 1
	v_addc_co_u32_e32 v229, vcc, 0, v7, vcc
	v_add_co_u32_e32 v230, vcc, 0x1e3000, v6
	s_nop 1
	v_addc_co_u32_e32 v231, vcc, 0, v7, vcc
	global_load_dword v232, v[216:217], off
	global_load_dword v233, v[218:219], off offset:1024
	global_load_dword v234, v[220:221], off offset:2048
	global_load_dword v235, v[222:223], off offset:3072
	global_load_dword v240, v[224:225], off
	global_load_dword v241, v[226:227], off offset:1024
	global_load_dword v242, v[228:229], off offset:2048
	global_load_dword v243, v[230:231], off offset:3072
	s_waitcnt vmcnt(15)
	v_add_f32_e32 v3, 0, v3
	s_waitcnt vmcnt(14)
	v_add_f32_e32 v3, v3, v22
	s_waitcnt vmcnt(13)
	v_add_f32_e32 v3, v3, v23
	s_waitcnt vmcnt(12)
	v_add_f32_e32 v3, v3, v24
	s_waitcnt vmcnt(11)
	v_add_f32_e32 v3, v3, v25
	s_waitcnt vmcnt(10)
	v_add_f32_e32 v3, v3, v26
	s_waitcnt vmcnt(9)
	v_add_f32_e32 v3, v3, v27
	s_waitcnt vmcnt(8)
	v_add_f32_e32 v3, v3, v28
	s_load_dwordx2 s[8:9], s[0:1], 0xf8
	v_and_b32_e32 v8, 0x3f0, v0
	v_lshlrev_b32_e32 v0, 1, v8
	s_waitcnt lgkmcnt(0)
	v_lshl_add_u64 v[4:5], s[8:9], 0, v[4:5]
	v_lshl_add_u64 v[12:13], v[4:5], 0, v[0:1]
	global_load_dwordx4 v[4:7], v[12:13], off
	global_load_dwordx4 v[212:215], v[12:13], off offset:16
	v_lshlrev_b32_e32 v0, 2, v8
	global_load_dwordx4 v[8:11], v0, s[40:41]
	global_load_dwordx4 v[200:203], v0, s[40:41] offset:16
	global_load_dwordx4 v[204:207], v0, s[40:41] offset:32
	global_load_dwordx4 v[208:211], v0, s[40:41] offset:48
	s_mov_b32 s8, 0x800000
	s_waitcnt vmcnt(13)
	v_add_f32_e32 v3, v3, v232
	s_waitcnt vmcnt(12)
	v_add_f32_e32 v3, v3, v233
	s_waitcnt vmcnt(11)
	v_add_f32_e32 v3, v3, v234
	s_waitcnt vmcnt(10)
	v_add_f32_e32 v3, v3, v235
	s_waitcnt vmcnt(9)
	v_add_f32_e32 v3, v3, v240
	s_waitcnt vmcnt(8)
	v_add_f32_e32 v3, v3, v241
	s_waitcnt vmcnt(7)
	v_add_f32_e32 v3, v3, v242
	s_waitcnt vmcnt(6)
	v_add_f32_e32 v3, v3, v243
	v_fmamk_f32 v3, v3, 0x3a800000, v180
	v_mul_f32_e32 v14, 0x4b800000, v3
	v_cmp_gt_f32_e32 vcc, s8, v3
	s_nop 1
	v_cndmask_b32_e32 v3, v3, v14, vcc
	v_rsq_f32_e32 v3, v3
	v_mul_f32_e32 v16, 0x45800000, v3
	v_cndmask_b32_e32 v16, v3, v16, vcc
	v_ashrrev_i32_e32 v3, 31, v2
	v_lshlrev_b64 v[2:3], 12, v[2:3]
	v_lshl_add_u64 v[2:3], s[42:43], 0, v[2:3]
	v_lshl_add_u64 v[18:19], v[2:3], 0, v[0:1]
	s_waitcnt vmcnt(5)
	v_lshlrev_b32_e32 v2, 16, v4
	v_and_b32_e32 v3, 0xffff0000, v4
	v_lshlrev_b32_e32 v4, 16, v5
	v_and_b32_e32 v5, 0xffff0000, v5
	v_pk_mul_f32 v[2:3], v[16:17], v[2:3] op_sel_hi:[0,1]
	v_pk_mul_f32 v[4:5], v[16:17], v[4:5] op_sel_hi:[0,1]
	s_waitcnt vmcnt(3)
	v_pk_mul_f32 v[2:3], v[2:3], v[8:9]
	v_pk_mul_f32 v[4:5], v[4:5], v[10:11]
	global_store_dwordx4 v[18:19], v[2:5], off
	v_lshlrev_b32_e32 v8, 16, v6
	v_and_b32_e32 v9, 0xffff0000, v6
	v_lshlrev_b32_e32 v6, 16, v7
	v_and_b32_e32 v7, 0xffff0000, v7
	v_pk_mul_f32 v[8:9], v[16:17], v[8:9] op_sel_hi:[0,1]
	v_pk_mul_f32 v[6:7], v[16:17], v[6:7] op_sel_hi:[0,1]
	s_waitcnt vmcnt(3)
	v_pk_mul_f32 v[2:3], v[8:9], v[200:201]
	v_pk_mul_f32 v[4:5], v[6:7], v[202:203]
	global_store_dwordx4 v[18:19], v[2:5], off offset:16
	v_lshlrev_b32_e32 v6, 16, v212
	v_and_b32_e32 v7, 0xffff0000, v212
	v_lshlrev_b32_e32 v8, 16, v213
	v_and_b32_e32 v9, 0xffff0000, v213
	v_pk_mul_f32 v[6:7], v[16:17], v[6:7] op_sel_hi:[0,1]
	v_pk_mul_f32 v[8:9], v[16:17], v[8:9] op_sel_hi:[0,1]
	s_waitcnt vmcnt(3)
	v_pk_mul_f32 v[2:3], v[6:7], v[204:205]
	v_pk_mul_f32 v[4:5], v[8:9], v[206:207]
	global_store_dwordx4 v[18:19], v[2:5], off offset:32
	v_lshlrev_b32_e32 v6, 16, v214
	v_and_b32_e32 v7, 0xffff0000, v214
	v_lshlrev_b32_e32 v8, 16, v215
	v_and_b32_e32 v9, 0xffff0000, v215
	v_pk_mul_f32 v[6:7], v[16:17], v[6:7] op_sel_hi:[0,1]
	v_pk_mul_f32 v[8:9], v[16:17], v[8:9] op_sel_hi:[0,1]
	s_waitcnt vmcnt(3)
	v_pk_mul_f32 v[2:3], v[6:7], v[208:209]
	v_pk_mul_f32 v[4:5], v[8:9], v[210:211]
	global_store_dwordx4 v[18:19], v[2:5], off offset:48
	s_cbranch_scc1 .LBB0_22

;     ...
;     auto issue_at = [&](int mm0, int nn0, int kt, int buf) {
;       char* lb = L0 + buf * BUFB;
; #pragma unroll
;       for (int i = 0; i < 4; ++i) {
;         const int seg = wv * 4 + i, row = seg * 8 + gl_row;
;         const int c = (lane & 7) ^ ((row >> 1) & 7);
;         const u16* ap = (kt < g.split) ? g.a0 + (size_t)(mm0 + row) * g.ld0 + kt * g.ks0 : g.a1 + (size_t)(mm0 + row) * g.ld1 + (kt - g.split) * 64;
;         __builtin_amdgcn_global_load_lds((const unsigned*)(ap + c * 8), (__attribute__((address_space(3))) unsigned*)(lb + seg * 1024 + lane * 16), 16, 0, 0);
;       }
; #pragma unroll
;       for (int i = 0; i < BN / 64; ++i) {
;         const int seg = wv * (BN / 64) + i, row = seg * 8 + gl_row;
;         const int c = (lane & 7) ^ ((row >> 1) & 7);
;         __builtin_amdgcn_global_load_lds((const unsigned*)(g.W + (size_t)(nn0 + row) * g.K + kt * 64 + c * 8),
;                                          (__attribute__((address_space(3))) unsigned*)(lb + 256 * 128 + seg * 1024 + lane * 16), 16, 0, 0);
;       }
;     };
;     ...
;       if (!(chain & 1)) {
;         issue(0, 0);
;         asm volatile("s_waitcnt vmcnt(0)" ::: "memory");
;         __syncthreads();
;       }
;       for (int kt = 0; kt < nk; ++kt) {
;         const int buf = kt & 1;
;         if (kt + 1 < nk) issue(kt + 1, buf ^ 1);
.LBB0_67:
	s_lshl_b32 s10, s46, 5
	s_waitcnt vmcnt(4)
	v_mov_b32_e32 v14, v179
	s_and_b32 s10, s10, 0x200
	s_sub_i32 s11, s17, s10
	s_waitcnt vmcnt(3)
	v_ashrrev_i32_e32 v6, 6, v14
	s_lshr_b32 s10, s46, 1
	v_lshrrev_b32_e32 v0, 30, v6
	s_and_b32 s10, s10, 8
	s_and_b32 s47, s46, 7
	v_add_u32_e32 v0, v6, v0
	s_or_b32 s10, s10, s47
	v_ashrrev_i32_e32 v147, 2, v0
	s_lshl_b32 s10, s10, 11
	v_mul_i32_i24_e32 v0, 4, v147
	s_waitcnt vmcnt(2)
	v_bfe_u32 v10, v14, 3, 3
	v_lshlrev_b32_e32 v11, 5, v6
	s_or_b32 s10, s10, s71
	v_sub_u32_e32 v149, v6, v0
	v_or_b32_e32 v0, v10, v11
	v_bfe_u32 v2, v14, 4, 2
	v_and_b32_e32 v7, 63, v14
	v_xor_b32_e32 v8, v2, v14
	v_add_u32_e32 v0, s10, v0
	v_mov_b64_e32 v[2:3], s[8:9]
	v_lshlrev_b32_e32 v12, 12, v6
	v_mad_i64_i32 v[4:5], s[48:49], v0, s88, v[2:3]
	v_lshlrev_b32_e32 v0, 4, v8
	v_lshlrev_b32_e32 v13, 4, v7
	v_and_b32_e32 v0, 0x70, v0
	v_add3_u32 v15, 0, v12, v13
	s_waitcnt vmcnt(1)
	v_lshlrev_b32_e32 v16, 2, v6
	v_lshl_add_u64 v[130:131], v[4:5], 0, v[0:1]
	s_mov_b64 s[52:53], 0xe00
	v_readfirstlane_b32 s47, v15
	v_or_b32_e32 v8, 1, v16
	v_lshl_add_u64 v[4:5], v[130:131], 0, s[52:53]
	s_mov_b32 m0, s47
	v_lshl_or_b32 v17, v8, 3, v10
	global_load_lds_dwordx4 v[4:5], off
	v_lshrrev_b32_e32 v4, 1, v17
	v_xor_b32_e32 v6, v4, v14
	v_add_u32_e32 v4, s10, v17
	v_lshlrev_b32_e32 v6, 4, v6
	v_lshlrev_b32_e32 v18, 10, v8
	v_mad_i64_i32 v[4:5], s[48:49], v4, s88, v[2:3]
	v_and_b32_e32 v6, 0x70, v6
	v_mov_b32_e32 v7, v1
	v_add3_u32 v19, 0, v18, v13
	v_lshl_add_u64 v[132:133], v[4:5], 0, v[6:7]
	v_readfirstlane_b32 s48, v19
	s_waitcnt vmcnt(0)
	v_or_b32_e32 v20, 2, v16
	v_lshl_add_u64 v[4:5], v[132:133], 0, s[52:53]
	s_mov_b32 m0, s48
	v_lshl_or_b32 v21, v20, 3, v10
	global_load_lds_dwordx4 v[4:5], off
	v_lshrrev_b32_e32 v4, 1, v21
	v_xor_b32_e32 v8, v4, v14
	v_add_u32_e32 v4, s10, v21
	v_lshlrev_b32_e32 v8, 4, v8
	v_lshlrev_b32_e32 v20, 10, v20
	v_mad_i64_i32 v[4:5], s[50:51], v4, s88, v[2:3]
	v_and_b32_e32 v8, 0x70, v8
	v_mov_b32_e32 v9, v1
	v_add3_u32 v22, 0, v20, v13
	v_lshl_add_u64 v[134:135], v[4:5], 0, v[8:9]
	v_readfirstlane_b32 s49, v22
	v_or_b32_e32 v16, 3, v16
	v_lshl_add_u64 v[4:5], v[134:135], 0, s[52:53]
	s_mov_b32 m0, s49
	v_lshl_or_b32 v23, v16, 3, v10
	global_load_lds_dwordx4 v[4:5], off
	v_add_u32_e32 v4, s10, v23
	v_mad_i64_i32 v[2:3], s[50:51], v4, s88, v[2:3]
	v_lshrrev_b32_e32 v4, 1, v23
	v_xor_b32_e32 v4, v4, v14
	v_lshlrev_b32_e32 v4, 4, v4
	v_lshlrev_b32_e32 v16, 10, v16
	v_and_b32_e32 v4, 0x70, v4
	v_mov_b32_e32 v5, v1
	v_add3_u32 v24, 0, v16, v13
	v_lshl_add_u64 v[136:137], v[2:3], 0, v[4:5]
	v_readfirstlane_b32 s50, v24
	s_and_b32 s11, s11, 0xffffff00
	v_lshl_add_u64 v[2:3], v[136:137], 0, s[52:53]
	s_mov_b32 m0, s50
	s_movk_i32 s56, 0x180
	global_load_lds_dwordx4 v[2:3], off
	v_add_u32_e32 v2, s11, v11
	v_or_b32_e32 v10, v2, v10
	v_mov_b64_e32 v[2:3], s[44:45]
	v_mad_i64_i32 v[10:11], s[52:53], v10, s56, v[2:3]
	v_lshl_add_u64 v[138:139], v[10:11], 0, v[0:1]
	v_add_u32_e32 v0, 0x8000, v15
	v_bfe_u32 v148, v14, 5, 1
	v_readfirstlane_b32 s51, v0
	v_add_u32_e32 v0, s11, v17
	v_mad_i64_i32 v[10:11], s[52:53], v0, s56, v[2:3]
	v_add_u32_e32 v0, 0x8000, v19
	v_lshl_add_u64 v[140:141], v[10:11], 0, v[6:7]
	v_readfirstlane_b32 s52, v0
	v_add_u32_e32 v0, s11, v21
	v_mad_i64_i32 v[6:7], s[54:55], v0, s56, v[2:3]
	v_add_u32_e32 v0, 0x8000, v22
	s_mov_b32 m0, s51
	v_readfirstlane_b32 s53, v0
	v_add_u32_e32 v0, s11, v23
	global_load_lds_dwordx4 v[138:139], off
	s_mov_b32 m0, s52
	v_mad_i64_i32 v[2:3], s[54:55], v0, s56, v[2:3]
	v_add_u32_e32 v0, 0x8000, v24
	global_load_lds_dwordx4 v[140:141], off
	v_lshl_add_u64 v[142:143], v[6:7], 0, v[8:9]
	s_mov_b32 m0, s53
	v_lshl_add_u64 v[144:145], v[2:3], 0, v[4:5]
	v_readfirstlane_b32 s54, v0
	v_add3_u32 v4, s24, v12, v13
	global_load_lds_dwordx4 v[142:143], off
	s_mov_b32 m0, s54
	s_mov_b64 s[56:57], 0xe80
	v_readfirstlane_b32 s55, v4
	v_add3_u32 v4, s24, v18, v13
	global_load_lds_dwordx4 v[144:145], off
	v_lshl_add_u64 v[2:3], v[130:131], 0, s[56:57]
	s_mov_b32 m0, s55
	v_readfirstlane_b32 s55, v4
	v_add3_u32 v4, s24, v20, v13
	s_waitcnt vmcnt(0)
	s_waitcnt vmcnt(0) lgkmcnt(0)
	s_barrier
	global_load_lds_dwordx4 v[2:3], off
	v_lshl_add_u64 v[2:3], v[132:133], 0, s[56:57]
	s_mov_b32 m0, s55
	v_readfirstlane_b32 s55, v4
	v_add3_u32 v4, s24, v16, v13
	global_load_lds_dwordx4 v[2:3], off
	v_lshl_add_u64 v[2:3], v[134:135], 0, s[56:57]
	s_mov_b32 m0, s55
	v_readfirstlane_b32 s55, v4
	v_add3_u32 v4, s25, v12, v13
	global_load_lds_dwordx4 v[2:3], off
	v_lshl_add_u64 v[2:3], v[136:137], 0, s[56:57]
	s_mov_b32 m0, s55
	v_readfirstlane_b32 s55, v4
	v_add3_u32 v4, s25, v18, v13
	v_lshrrev_b32_e32 v0, 1, v14
	global_load_lds_dwordx4 v[2:3], off
	v_lshl_add_u64 v[2:3], v[138:139], 0, s[26:27]
	s_mov_b32 m0, s55
	v_readfirstlane_b32 s55, v4
	v_add3_u32 v4, s25, v20, v13
	v_and_b32_e32 v146, 31, v14
	v_bitop3_b32 v0, v0, v148, 7 bitop3:0x6c
	global_load_lds_dwordx4 v[2:3], off
	v_lshl_add_u64 v[2:3], v[140:141], 0, s[26:27]
	s_mov_b32 m0, s55
	v_readfirstlane_b32 s55, v4
	v_add3_u32 v4, s25, v16, v13
	v_lshlrev_b32_e32 v0, 4, v0
	v_lshlrev_b32_e32 v6, 7, v146
	global_load_lds_dwordx4 v[2:3], off
	v_lshl_add_u64 v[2:3], v[142:143], 0, s[26:27]
	s_mov_b32 m0, s55
	v_readfirstlane_b32 s55, v4
	v_lshl_or_b32 v162, v149, 13, v6
	global_load_lds_dwordx4 v[2:3], off
	v_lshl_add_u64 v[2:3], v[144:145], 0, s[26:27]
	s_mov_b32 m0, s55
	v_add_u32_e32 v7, 0, v0
	global_load_lds_dwordx4 v[2:3], off
	v_add_u32_e32 v163, v7, v162
	ds_read_b128 v[2:5], v163 offset:32768
	ds_read_b128 v[10:13], v163 offset:36864
	v_lshl_or_b32 v164, v147, 14, v6
	v_add_u32_e32 v165, v7, v164
	ds_read_b128 v[6:9], v165
	s_waitcnt lgkmcnt(0)
; #define MFMA(a, b, c) __builtin_amdgcn_mfma_f32_32x32x16_bf16((a), (b), (c), 0, 0, 0)
;     ...
;     auto compute2 = [&](int buf) {
;       const char* lb = L0 + buf * BUFB;
; #pragma unroll
;       for (int ks = 0; ks < 4; ++ks) {
;         const int c = ks * 2 + hh;
;         bf16x8 wf[2], xf[MI];
; #pragma unroll
;         for (int j = 0; j < 2; ++j) { const int r = wn * 64 + j * 32 + l32; wf[j] = *(const bf16x8*)(lb + 256 * 128 + r * 128 + ((c ^ ((r >> 1) & 7)) << 4)); }
; #pragma unroll
;         for (int i = 0; i < MI; ++i) { const int r = wm * (MI * 32) + i * 32 + l32; xf[i] = *(const bf16x8*)(lb + r * 128 + ((c ^ ((r >> 1) & 7)) << 4)); }
; #pragma unroll
;         for (int i = 0; i < MI; ++i) {
;           acc[i][0] = MFMA(wf[0], xf[i], acc[i][0]);
;           acc[i][1] = MFMA(wf[1], xf[i], acc[i][1]);
;         }
;       }
;     };
;     ...
;       for (int kt = 0; kt < nk; ++kt) {
;         const int buf = kt & 1;
;         if (kt + 1 < nk) issue(kt + 1, buf ^ 1);
;         else if (chain & 2) issue_at(nmt * 256, nnt * BN, 0, buf ^ 1);
;         compute2(buf);
;         asm volatile("s_waitcnt vmcnt(0)" ::: "memory");
;         __syncthreads();
;       }
	v_mfma_f32_32x32x16_bf16 v[114:129], v[2:5], v[6:9], 0
	v_bfe_u32 v166, v14, 1, 3
	s_mov_b64 s[56:57], 0xf00
	v_lshl_add_u64 v[130:131], v[130:131], 0, s[56:57]
	s_mov_b32 m0, s47
	v_mfma_f32_32x32x16_bf16 v[98:113], v[10:13], v[6:9], 0
	ds_read_b128 v[6:9], v165 offset:4096
	s_waitcnt lgkmcnt(0)
	v_mfma_f32_32x32x16_bf16 v[82:97], v[2:5], v[6:9], 0
	v_mfma_f32_32x32x16_bf16 v[66:81], v[10:13], v[6:9], 0
	ds_read_b128 v[6:9], v165 offset:8192
	s_waitcnt lgkmcnt(0)
	v_mfma_f32_32x32x16_bf16 v[50:65], v[2:5], v[6:9], 0
	v_mfma_f32_32x32x16_bf16 v[34:49], v[10:13], v[6:9], 0
	ds_read_b128 v[6:9], v165 offset:12288
	s_waitcnt lgkmcnt(0)
	v_mfma_f32_32x32x16_bf16 v[18:33], v[2:5], v[6:9], 0
	v_bitop3_b32 v2, v148, v166, 2 bitop3:0x36
	v_lshlrev_b32_e32 v167, 4, v2
	v_add_u32_e32 v154, 0, v167
	v_add_u32_e32 v168, v154, v162
	ds_read_b128 v[150:153], v168 offset:32768
	ds_read_b128 v[158:161], v168 offset:36864
	v_add_u32_e32 v169, v154, v164
	ds_read_b128 v[154:157], v169
	s_waitcnt lgkmcnt(0)
	v_mfma_f32_32x32x16_bf16 v[114:129], v[150:153], v[154:157], v[114:129]
	v_mfma_f32_32x32x16_bf16 v[98:113], v[158:161], v[154:157], v[98:113]
	ds_read_b128 v[154:157], v169 offset:4096
	s_waitcnt lgkmcnt(0)
	v_mfma_f32_32x32x16_bf16 v[82:97], v[150:153], v[154:157], v[82:97]
	v_mfma_f32_32x32x16_bf16 v[66:81], v[158:161], v[154:157], v[66:81]
	ds_read_b128 v[154:157], v169 offset:8192
	v_mfma_f32_32x32x16_bf16 v[2:17], v[10:13], v[6:9], 0
	s_waitcnt lgkmcnt(0)
	v_mfma_f32_32x32x16_bf16 v[50:65], v[150:153], v[154:157], v[50:65]
	v_mfma_f32_32x32x16_bf16 v[34:49], v[158:161], v[154:157], v[34:49]
	ds_read_b128 v[154:157], v169 offset:12288
	s_waitcnt lgkmcnt(0)
	v_mfma_f32_32x32x16_bf16 v[18:33], v[150:153], v[154:157], v[18:33]
	v_bitop3_b32 v150, v148, v166, 4 bitop3:0x36
	v_lshlrev_b32_e32 v170, 4, v150
	v_mfma_f32_32x32x16_bf16 v[2:17], v[158:161], v[154:157], v[2:17]
	v_add_u32_e32 v154, 0, v170
	v_add_u32_e32 v171, v154, v162
	ds_read_b128 v[150:153], v171 offset:32768
	ds_read_b128 v[158:161], v171 offset:36864
	v_add_u32_e32 v172, v154, v164
	ds_read_b128 v[154:157], v172
	s_waitcnt lgkmcnt(0)
	v_mfma_f32_32x32x16_bf16 v[114:129], v[150:153], v[154:157], v[114:129]
	v_mfma_f32_32x32x16_bf16 v[98:113], v[158:161], v[154:157], v[98:113]
	ds_read_b128 v[154:157], v172 offset:4096
	s_waitcnt lgkmcnt(0)
	v_mfma_f32_32x32x16_bf16 v[82:97], v[150:153], v[154:157], v[82:97]
	v_mfma_f32_32x32x16_bf16 v[66:81], v[158:161], v[154:157], v[66:81]
	ds_read_b128 v[154:157], v172 offset:8192
	s_waitcnt lgkmcnt(0)
	v_mfma_f32_32x32x16_bf16 v[50:65], v[150:153], v[154:157], v[50:65]
	v_mfma_f32_32x32x16_bf16 v[34:49], v[158:161], v[154:157], v[34:49]
	ds_read_b128 v[154:157], v172 offset:12288
	s_waitcnt lgkmcnt(0)
	v_mfma_f32_32x32x16_bf16 v[18:33], v[150:153], v[154:157], v[18:33]
	v_bitop3_b32 v150, v148, v166, 6 bitop3:0x36
	v_lshlrev_b32_e32 v166, 4, v150
	v_mfma_f32_32x32x16_bf16 v[2:17], v[158:161], v[154:157], v[2:17]
	v_add_u32_e32 v154, 0, v166
	v_add_u32_e32 v173, v154, v162
	ds_read_b128 v[150:153], v173 offset:32768
	ds_read_b128 v[158:161], v173 offset:36864
	v_add_u32_e32 v174, v154, v164
	ds_read_b128 v[154:157], v174
	s_waitcnt lgkmcnt(0)
	v_mfma_f32_32x32x16_bf16 v[114:129], v[150:153], v[154:157], v[114:129]
	v_mfma_f32_32x32x16_bf16 v[98:113], v[158:161], v[154:157], v[98:113]
	ds_read_b128 v[154:157], v174 offset:4096
	s_waitcnt lgkmcnt(0)
	v_mfma_f32_32x32x16_bf16 v[82:97], v[150:153], v[154:157], v[82:97]
	v_mfma_f32_32x32x16_bf16 v[66:81], v[158:161], v[154:157], v[66:81]
	ds_read_b128 v[154:157], v174 offset:8192
	s_waitcnt lgkmcnt(0)
	v_mfma_f32_32x32x16_bf16 v[50:65], v[150:153], v[154:157], v[50:65]
	v_mfma_f32_32x32x16_bf16 v[34:49], v[158:161], v[154:157], v[34:49]
	ds_read_b128 v[154:157], v174 offset:12288
	s_waitcnt vmcnt(0)
	s_waitcnt vmcnt(0) lgkmcnt(0)
	s_barrier
	global_load_lds_dwordx4 v[130:131], off
	v_lshl_add_u64 v[130:131], v[132:133], 0, s[56:57]
	s_mov_b32 m0, s48
	v_mfma_f32_32x32x16_bf16 v[18:33], v[150:153], v[154:157], v[18:33]
	global_load_lds_dwordx4 v[130:131], off
	v_lshl_add_u64 v[130:131], v[134:135], 0, s[56:57]
	s_mov_b32 m0, s49
	s_nop 0
	global_load_lds_dwordx4 v[130:131], off
	v_lshl_add_u64 v[130:131], v[136:137], 0, s[56:57]
	s_mov_b32 m0, s50
	v_mfma_f32_32x32x16_bf16 v[2:17], v[158:161], v[154:157], v[2:17]
	global_load_lds_dwordx4 v[130:131], off
	v_lshl_add_u64 v[130:131], v[138:139], 0, s[90:91]
	s_mov_b32 m0, s51
	v_add3_u32 v138, s25, v0, v162
	global_load_lds_dwordx4 v[130:131], off
	v_lshl_add_u64 v[130:131], v[140:141], 0, s[90:91]
	s_mov_b32 m0, s52
	v_add3_u32 v0, s24, v0, v164
	global_load_lds_dwordx4 v[130:131], off
	v_lshl_add_u64 v[130:131], v[142:143], 0, s[90:91]
	s_mov_b32 m0, s53
	v_add3_u32 v142, s24, v167, v164
	global_load_lds_dwordx4 v[130:131], off
	v_lshl_add_u64 v[130:131], v[144:145], 0, s[90:91]
	s_mov_b32 m0, s54
	s_nop 0
	global_load_lds_dwordx4 v[130:131], off
	ds_read_b128 v[130:133], v138
	ds_read_b128 v[134:137], v0
	ds_read_b128 v[138:141], v138 offset:4096
	s_waitcnt lgkmcnt(0)
	v_mfma_f32_32x32x16_bf16 v[114:129], v[130:133], v[134:137], v[114:129]
	v_mfma_f32_32x32x16_bf16 v[98:113], v[138:141], v[134:137], v[98:113]
	ds_read_b128 v[134:137], v0 offset:4096
	s_waitcnt lgkmcnt(0)
	v_mfma_f32_32x32x16_bf16 v[82:97], v[130:133], v[134:137], v[82:97]
	v_mfma_f32_32x32x16_bf16 v[66:81], v[138:141], v[134:137], v[66:81]
	ds_read_b128 v[134:137], v0 offset:8192
	s_waitcnt lgkmcnt(0)
	v_mfma_f32_32x32x16_bf16 v[50:65], v[130:133], v[134:137], v[50:65]
	v_mfma_f32_32x32x16_bf16 v[34:49], v[138:141], v[134:137], v[34:49]
	ds_read_b128 v[134:137], v0 offset:12288
	v_add3_u32 v0, s25, v167, v162
	s_waitcnt lgkmcnt(0)
; #define MFMA(a, b, c) __builtin_amdgcn_mfma_f32_32x32x16_bf16((a), (b), (c), 0, 0, 0)
;     ...
;     auto compute2 = [&](int buf) {
;       const char* lb = L0 + buf * BUFB;
; #pragma unroll
;       for (int ks = 0; ks < 4; ++ks) {
;         const int c = ks * 2 + hh;
;         bf16x8 wf[2], xf[MI];
; #pragma unroll
;         for (int j = 0; j < 2; ++j) { const int r = wn * 64 + j * 32 + l32; wf[j] = *(const bf16x8*)(lb + 256 * 128 + r * 128 + ((c ^ ((r >> 1) & 7)) << 4)); }
; #pragma unroll
;         for (int i = 0; i < MI; ++i) { const int r = wm * (MI * 32) + i * 32 + l32; xf[i] = *(const bf16x8*)(lb + r * 128 + ((c ^ ((r >> 1) & 7)) << 4)); }
; #pragma unroll
;         for (int i = 0; i < MI; ++i) {
;           acc[i][0] = MFMA(wf[0], xf[i], acc[i][0]);
;           acc[i][1] = MFMA(wf[1], xf[i], acc[i][1]);
;         }
;       }
;     };
;     if (NBUF == 3) {
;       issue(0, 0);
;       if (nk > 1) { issue(1, 1); if (BN == 128) asm volatile("s_waitcnt vmcnt(6)" ::: "memory"); else asm volatile("s_waitcnt vmcnt(5)" ::: "memory"); }
;       else asm volatile("s_waitcnt vmcnt(0)" ::: "memory");
;       asm volatile("s_waitcnt lgkmcnt(0)" ::: "memory");
;       __builtin_amdgcn_s_barrier();
;       int buf = 0;
;       for (int kt = 0; kt < nk; ++kt) {
;         const int b2 = buf == 0 ? 2 : buf - 1;
;         if (kt + 2 < nk) issue(kt + 2, b2);
;         compute2(buf);
;         if (kt + 2 < nk) { if (BN == 128) asm volatile("s_waitcnt vmcnt(6)" ::: "memory"); else asm volatile("s_waitcnt vmcnt(5)" ::: "memory"); }
;         else asm volatile("s_waitcnt vmcnt(0)" ::: "memory");
;         asm volatile("s_waitcnt lgkmcnt(0)" ::: "memory");
;         __builtin_amdgcn_s_barrier();
;         buf = buf == 2 ? 0 : buf + 1;
;       }
;     } else {
;       if (!(chain & 1)) {
;         issue(0, 0);
;         asm volatile("s_waitcnt vmcnt(0)" ::: "memory");
;         __syncthreads();
;       }
;       for (int kt = 0; kt < nk; ++kt) {
;         const int buf = kt & 1;
;         if (kt + 1 < nk) issue(kt + 1, buf ^ 1);
;         else if (chain & 2) issue_at(nmt * 256, nnt * BN, 0, buf ^ 1);
;         compute2(buf);
;         asm volatile("s_waitcnt vmcnt(0)" ::: "memory");
;         __syncthreads();
;       }
;     }
;     __syncthreads();
	v_mfma_f32_32x32x16_bf16 v[18:33], v[130:133], v[134:137], v[18:33]
	ds_read_b128 v[130:133], v0
	v_mfma_f32_32x32x16_bf16 v[2:17], v[138:141], v[134:137], v[2:17]
	ds_read_b128 v[138:141], v0 offset:4096
	ds_read_b128 v[134:137], v142
	v_add3_u32 v0, s25, v170, v162
	s_waitcnt lgkmcnt(0)
	v_mfma_f32_32x32x16_bf16 v[114:129], v[130:133], v[134:137], v[114:129]
	v_mfma_f32_32x32x16_bf16 v[98:113], v[138:141], v[134:137], v[98:113]
	ds_read_b128 v[134:137], v142 offset:4096
	s_waitcnt lgkmcnt(0)
	v_mfma_f32_32x32x16_bf16 v[82:97], v[130:133], v[134:137], v[82:97]
	v_mfma_f32_32x32x16_bf16 v[66:81], v[138:141], v[134:137], v[66:81]
	ds_read_b128 v[134:137], v142 offset:8192
	s_waitcnt lgkmcnt(0)
	v_mfma_f32_32x32x16_bf16 v[50:65], v[130:133], v[134:137], v[50:65]
	v_mfma_f32_32x32x16_bf16 v[34:49], v[138:141], v[134:137], v[34:49]
	ds_read_b128 v[134:137], v142 offset:12288
	v_add3_u32 v142, s24, v170, v164
	s_waitcnt lgkmcnt(0)
	v_mfma_f32_32x32x16_bf16 v[18:33], v[130:133], v[134:137], v[18:33]
	ds_read_b128 v[130:133], v0
	v_mfma_f32_32x32x16_bf16 v[2:17], v[138:141], v[134:137], v[2:17]
	ds_read_b128 v[138:141], v0 offset:4096
	ds_read_b128 v[134:137], v142
	v_add3_u32 v0, s25, v166, v162
	s_waitcnt lgkmcnt(0)
	v_mfma_f32_32x32x16_bf16 v[114:129], v[130:133], v[134:137], v[114:129]
	v_mfma_f32_32x32x16_bf16 v[98:113], v[138:141], v[134:137], v[98:113]
	ds_read_b128 v[134:137], v142 offset:4096
	s_waitcnt lgkmcnt(0)
	v_mfma_f32_32x32x16_bf16 v[82:97], v[130:133], v[134:137], v[82:97]
	v_mfma_f32_32x32x16_bf16 v[66:81], v[138:141], v[134:137], v[66:81]
	ds_read_b128 v[134:137], v142 offset:8192
	s_waitcnt lgkmcnt(0)
	v_mfma_f32_32x32x16_bf16 v[50:65], v[130:133], v[134:137], v[50:65]
	v_mfma_f32_32x32x16_bf16 v[34:49], v[138:141], v[134:137], v[34:49]
	ds_read_b128 v[134:137], v142 offset:12288
	v_add3_u32 v142, s24, v166, v164
	s_waitcnt lgkmcnt(0)
	v_mfma_f32_32x32x16_bf16 v[18:33], v[130:133], v[134:137], v[18:33]
	ds_read_b128 v[130:133], v0
	v_mfma_f32_32x32x16_bf16 v[2:17], v[138:141], v[134:137], v[2:17]
	ds_read_b128 v[138:141], v0 offset:4096
	ds_read_b128 v[134:137], v142
	v_lshl_add_u32 v0, v149, 6, s11
	s_waitcnt lgkmcnt(0)
	v_mfma_f32_32x32x16_bf16 v[114:129], v[130:133], v[134:137], v[114:129]
	v_mfma_f32_32x32x16_bf16 v[98:113], v[138:141], v[134:137], v[98:113]
	ds_read_b128 v[134:137], v142 offset:4096
	s_waitcnt lgkmcnt(0)
	v_mfma_f32_32x32x16_bf16 v[82:97], v[130:133], v[134:137], v[82:97]
	v_mfma_f32_32x32x16_bf16 v[66:81], v[138:141], v[134:137], v[66:81]
	ds_read_b128 v[134:137], v142 offset:8192
	s_waitcnt lgkmcnt(0)
	v_mfma_f32_32x32x16_bf16 v[50:65], v[130:133], v[134:137], v[50:65]
	v_mfma_f32_32x32x16_bf16 v[34:49], v[138:141], v[134:137], v[34:49]
	ds_read_b128 v[134:137], v142 offset:12288
	s_waitcnt vmcnt(0)
	s_waitcnt vmcnt(0) lgkmcnt(0)
	s_barrier
	v_mfma_f32_32x32x16_bf16 v[18:33], v[130:133], v[134:137], v[18:33]
	v_mfma_f32_32x32x16_bf16 v[2:17], v[138:141], v[134:137], v[2:17]
	ds_read_b128 v[130:133], v163 offset:32768
	ds_read_b128 v[134:137], v165
	ds_read_b128 v[138:141], v163 offset:36864
	s_waitcnt lgkmcnt(1)
	v_mfma_f32_32x32x16_bf16 v[114:129], v[130:133], v[134:137], v[114:129]
	s_waitcnt lgkmcnt(0)
	v_mfma_f32_32x32x16_bf16 v[98:113], v[138:141], v[134:137], v[98:113]
	ds_read_b128 v[134:137], v165 offset:4096
	s_waitcnt lgkmcnt(0)
	v_mfma_f32_32x32x16_bf16 v[82:97], v[130:133], v[134:137], v[82:97]
	v_mfma_f32_32x32x16_bf16 v[66:81], v[138:141], v[134:137], v[66:81]
	ds_read_b128 v[134:137], v165 offset:8192
	s_waitcnt lgkmcnt(0)
	v_mfma_f32_32x32x16_bf16 v[50:65], v[130:133], v[134:137], v[50:65]
	v_mfma_f32_32x32x16_bf16 v[34:49], v[138:141], v[134:137], v[34:49]
	ds_read_b128 v[134:137], v165 offset:12288
	s_waitcnt lgkmcnt(0)
	v_mfma_f32_32x32x16_bf16 v[18:33], v[130:133], v[134:137], v[18:33]
	v_mfma_f32_32x32x16_bf16 v[2:17], v[138:141], v[134:137], v[2:17]
	ds_read_b128 v[130:133], v168 offset:32768
	ds_read_b128 v[134:137], v169
	ds_read_b128 v[138:141], v168 offset:36864
	s_waitcnt lgkmcnt(1)
	v_mfma_f32_32x32x16_bf16 v[114:129], v[130:133], v[134:137], v[114:129]
	s_waitcnt lgkmcnt(0)
	v_mfma_f32_32x32x16_bf16 v[98:113], v[138:141], v[134:137], v[98:113]
	ds_read_b128 v[134:137], v169 offset:4096
	s_waitcnt lgkmcnt(0)
	v_mfma_f32_32x32x16_bf16 v[82:97], v[130:133], v[134:137], v[82:97]
	v_mfma_f32_32x32x16_bf16 v[66:81], v[138:141], v[134:137], v[66:81]
	ds_read_b128 v[134:137], v169 offset:8192
	s_waitcnt lgkmcnt(0)
	v_mfma_f32_32x32x16_bf16 v[50:65], v[130:133], v[134:137], v[50:65]
	v_mfma_f32_32x32x16_bf16 v[34:49], v[138:141], v[134:137], v[34:49]
	ds_read_b128 v[134:137], v169 offset:12288
	s_waitcnt lgkmcnt(0)
	v_mfma_f32_32x32x16_bf16 v[18:33], v[130:133], v[134:137], v[18:33]
	v_mfma_f32_32x32x16_bf16 v[2:17], v[138:141], v[134:137], v[2:17]
	ds_read_b128 v[130:133], v171 offset:32768
	ds_read_b128 v[134:137], v172
	ds_read_b128 v[138:141], v171 offset:36864
	s_waitcnt lgkmcnt(1)
	v_mfma_f32_32x32x16_bf16 v[114:129], v[130:133], v[134:137], v[114:129]
	s_waitcnt lgkmcnt(0)
	v_mfma_f32_32x32x16_bf16 v[98:113], v[138:141], v[134:137], v[98:113]
	ds_read_b128 v[134:137], v172 offset:4096
	s_waitcnt lgkmcnt(0)
	v_mfma_f32_32x32x16_bf16 v[82:97], v[130:133], v[134:137], v[82:97]
	v_mfma_f32_32x32x16_bf16 v[66:81], v[138:141], v[134:137], v[66:81]
	ds_read_b128 v[134:137], v172 offset:8192
	s_waitcnt lgkmcnt(0)
	v_mfma_f32_32x32x16_bf16 v[50:65], v[130:133], v[134:137], v[50:65]
	v_mfma_f32_32x32x16_bf16 v[34:49], v[138:141], v[134:137], v[34:49]
	ds_read_b128 v[134:137], v172 offset:12288
	s_waitcnt lgkmcnt(0)
	v_mfma_f32_32x32x16_bf16 v[18:33], v[130:133], v[134:137], v[18:33]
	v_mfma_f32_32x32x16_bf16 v[2:17], v[138:141], v[134:137], v[2:17]
	ds_read_b128 v[130:133], v173 offset:32768
	ds_read_b128 v[134:137], v174
	ds_read_b128 v[138:141], v173 offset:36864
	ds_read_b128 v[142:145], v174 offset:12288
	s_waitcnt lgkmcnt(2)
	v_mfma_f32_32x32x16_bf16 v[114:129], v[130:133], v[134:137], v[114:129]
	s_waitcnt lgkmcnt(1)
	v_mfma_f32_32x32x16_bf16 v[98:113], v[138:141], v[134:137], v[98:113]
	ds_read_b128 v[134:137], v174 offset:4096
	s_waitcnt lgkmcnt(0)
	v_mfma_f32_32x32x16_bf16 v[82:97], v[130:133], v[134:137], v[82:97]
	v_mfma_f32_32x32x16_bf16 v[66:81], v[138:141], v[134:137], v[66:81]
	ds_read_b128 v[134:137], v174 offset:8192
	s_waitcnt vmcnt(0)
	s_waitcnt lgkmcnt(0)
	s_barrier
; DI float bflo(unsigned u) { return __uint_as_float(u << 16); }
; DI float bfhi(unsigned u) { return __uint_as_float(u & 0xffff0000u); }
;     ...
;     } else if (EPI == EPI_POST) {
;       if (m < T) {
;         int s, pos, L; row2seq(m, s, pos, L);
;         const int hd = nw >> 6;
;         u16* yb = (u16*)p.out + (size_t)m * 1024;
;         float y[2][16];
;         float sum = 0.f;
; #pragma unroll
;         for (int j = 0; j < 2; ++j)
; #pragma unroll
;           for (int gq = 0; gq < 4; ++gq) {
;             int n = nw + j * 32 + 8 * gq + 4 * hh;
;             uint2 a = *(const uint2*)(yb + n), b = *(const uint2*)(yb + 512 + n);
;             y[j][4 * gq + 0] = bflo(a.x) + bflo(b.x); y[j][4 * gq + 1] = bfhi(a.x) + bfhi(b.x);
;             y[j][4 * gq + 2] = bflo(a.y) + bflo(b.y); y[j][4 * gq + 3] = bfhi(a.y) + bfhi(b.y);
;             sum += y[j][4 * gq] + y[j][4 * gq + 1] + y[j][4 * gq + 2] + y[j][4 * gq + 3];
;           }
;         sum += __shfl_xor(sum, 32);
;         const float mu = sum * (1.f / 64.f);
;         float vs = 0.f;
; #pragma unroll
;         for (int j = 0; j < 2; ++j)
; #pragma unroll
;           for (int r = 0; r < 16; ++r) { float dlt = y[j][r] - mu; vs += dlt * dlt; }
;         vs += __shfl_xor(vs, 32);
;         const float rstd = rsqrtf(vs * (1.f / 64.f) + LNX_EPS);
;         const float bsum = p.bsc[(size_t)m * 8 + hd] + p.bsc[((size_t)TP + m) * 8 + hd];
;         const u16* vb = p.regB + (size_t)m * 1952 + 1024;
	v_mfma_f32_32x32x16_bf16 v[50:65], v[130:133], v[134:137], v[50:65]
	v_mfma_f32_32x32x16_bf16 v[34:49], v[138:141], v[134:137], v[34:49]
	v_lshl_add_u32 v134, v147, 7, s10
	v_or_b32_e32 v136, v134, v146
	v_lshl_or_b32 v134, v148, 2, v0
	s_mov_b32 s10, 0x80a0
	v_cmp_gt_i32_e32 vcc, s10, v136
	v_ashrrev_i32_e32 v135, 31, v134
	v_mfma_f32_32x32x16_bf16 v[18:33], v[130:133], v[142:145], v[18:33]
	v_ashrrev_i32_e32 v132, 6, v0
	v_add_u32_e32 v130, s15, v134
	v_ashrrev_i32_e32 v133, 31, v132
	v_ashrrev_i32_e32 v131, 31, v130
	v_mfma_f32_32x32x16_bf16 v[2:17], v[138:141], v[142:145], v[2:17]
	s_and_saveexec_b64 s[10:11], vcc
	s_cbranch_execz .LBB0_69
	v_ashrrev_i32_e32 v137, 31, v136
	v_lshlrev_b64 v[138:139], 11, v[136:137]
	v_lshl_add_u64 v[138:139], s[78:79], 0, v[138:139]
	v_lshlrev_b64 v[140:141], 1, v[134:135]
	v_lshl_add_u64 v[138:139], v[138:139], 0, v[140:141]
	global_load_dwordx2 v[142:143], v[138:139], off
	global_load_dwordx2 v[144:145], v[138:139], off offset:1024
	global_load_dwordx2 v[146:147], v[138:139], off offset:16
	global_load_dwordx2 v[148:149], v[138:139], off offset:1040
	global_load_dwordx2 v[150:151], v[138:139], off offset:32
	global_load_dwordx2 v[152:153], v[138:139], off offset:1056
	global_load_dwordx2 v[162:163], v[138:139], off offset:1072
	global_load_dwordx2 v[164:165], v[138:139], off offset:48
	global_load_dwordx2 v[154:155], v[138:139], off offset:80
	global_load_dwordx2 v[156:157], v[138:139], off offset:1104
	global_load_dwordx2 v[166:167], v[138:139], off offset:1120
	global_load_dwordx2 v[168:169], v[138:139], off offset:96
	v_and_b32_e32 v160, 64, v183
	v_xor_b32_e32 v0, 32, v183
	v_add_u32_e32 v170, 64, v160
	v_cmp_lt_i32_e32 vcc, v0, v170
	global_load_dwordx2 v[170:171], v[138:139], off offset:112
	global_load_dwordx2 v[172:173], v[138:139], off offset:64
	global_load_dwordx2 v[174:175], v[138:139], off offset:1136
	global_load_dwordx2 v[176:177], v[138:139], off offset:1088
	v_lshlrev_b64 v[160:161], 5, v[136:137]
	v_lshl_add_u64 v[160:161], s[2:3], 0, v[160:161]
	v_lshl_add_u64 v[160:161], v[132:133], 2, v[160:161]
	s_mov_b32 s47, 0x102000
	v_cndmask_b32_e32 v0, v183, v0, vcc
	v_add_co_u32_e32 v200, vcc, s47, v160
	v_mov_b64_e32 v[158:159], s[8:9]
	s_nop 0
	v_addc_co_u32_e32 v201, vcc, 0, v161, vcc
	global_load_dword v178, v[160:161], off
	global_load_dword v199, v[200:201], off
	v_lshlrev_b32_e32 v137, 2, v0
	s_mov_b32 s47, 0x800000
	s_waitcnt vmcnt(17)
	v_lshlrev_b32_e32 v160, 16, v142
	s_waitcnt vmcnt(16)
	v_lshlrev_b32_e32 v200, 16, v144
	v_and_b32_e32 v201, 0xffff0000, v144
	v_lshlrev_b32_e32 v204, 16, v145
	v_and_b32_e32 v205, 0xffff0000, v145
	s_waitcnt vmcnt(13)
	v_lshlrev_b32_e32 v144, 16, v150
	s_waitcnt vmcnt(12)
	v_lshlrev_b32_e32 v210, 16, v152
	v_and_b32_e32 v145, 0xffff0000, v150
	v_and_b32_e32 v211, 0xffff0000, v152
	v_and_b32_e32 v161, 0xffff0000, v142
	v_lshlrev_b32_e32 v202, 16, v143
	v_and_b32_e32 v203, 0xffff0000, v143
	v_and_b32_e32 v143, 0xffff0000, v148
	v_and_b32_e32 v142, 0xffff0000, v146
	v_lshlrev_b32_e32 v213, 16, v151
	v_lshlrev_b32_e32 v215, 16, v153
	v_and_b32_e32 v212, 0xffff0000, v151
	v_and_b32_e32 v214, 0xffff0000, v153
	s_waitcnt vmcnt(9)
	v_lshlrev_b32_e32 v216, 16, v154
	s_waitcnt vmcnt(8)
	v_lshlrev_b32_e32 v218, 16, v156
	v_and_b32_e32 v217, 0xffff0000, v154
	v_and_b32_e32 v219, 0xffff0000, v156
	v_pk_add_f32 v[210:211], v[144:145], v[210:211]
	v_lshlrev_b32_e32 v221, 16, v155
	v_lshlrev_b32_e32 v223, 16, v157
	v_and_b32_e32 v220, 0xffff0000, v155
	v_and_b32_e32 v222, 0xffff0000, v157
	v_pk_add_f32 v[228:229], v[142:143], v[142:143] op_sel:[1,0] op_sel_hi:[0,1]
	v_pk_add_f32 v[212:213], v[212:213], v[214:215]
	v_pk_add_f32 v[214:215], v[216:217], v[218:219]
	v_pk_add_f32 v[142:143], v[210:211], v[210:211] op_sel:[0,1] op_sel_hi:[1,0]
	v_pk_add_f32 v[216:217], v[220:221], v[222:223]
	v_pk_add_f32 v[144:145], v[214:215], v[214:215] op_sel:[0,1] op_sel_hi:[1,0]
	v_pk_add_f32 v[142:143], v[142:143], v[212:213] op_sel:[0,1] op_sel_hi:[1,0]
	v_pk_add_f32 v[144:145], v[144:145], v[216:217] op_sel:[0,1] op_sel_hi:[1,0]
	v_pk_add_f32 v[218:219], v[212:213], v[142:143]
	v_mad_i64_i32 v[142:143], s[48:49], v136, s88, v[158:159]
	v_pk_add_f32 v[220:221], v[216:217], v[144:145]
	v_lshl_add_u64 v[144:145], v[142:143], 0, v[140:141]
	v_lshlrev_b64 v[140:141], 2, v[130:131]
	v_lshl_add_u64 v[142:143], s[40:41], 0, v[140:141]
	global_load_dwordx2 v[222:223], v[144:145], off offset:2048
	v_lshl_add_u64 v[140:141], s[42:43], 0, v[140:141]
	v_pk_add_f32 v[200:201], v[160:161], v[200:201]
	global_load_dwordx4 v[154:157], v[142:143], off
	global_load_dwordx4 v[158:161], v[140:141], off
	v_lshlrev_b32_e32 v207, 16, v146
	v_lshlrev_b32_e32 v209, 16, v148
	v_lshlrev_b32_e32 v148, 16, v149
	v_lshlrev_b32_e32 v146, 16, v147
	v_and_b32_e32 v149, 0xffff0000, v149
	v_and_b32_e32 v147, 0xffff0000, v147
	v_pk_add_f32 v[202:203], v[202:203], v[204:205]
	v_mov_b32_e32 v206, v200
	v_mov_b32_e32 v208, v201
	v_lshlrev_b32_e32 v150, 16, v162
	v_lshlrev_b32_e32 v152, 16, v164
	v_and_b32_e32 v151, 0xffff0000, v162
	v_and_b32_e32 v153, 0xffff0000, v164
	v_pk_add_f32 v[204:205], v[206:207], v[208:209]
	v_mov_b32_e32 v206, v202
	v_mov_b32_e32 v207, v228
	s_waitcnt vmcnt(7)
	v_lshlrev_b32_e32 v209, 16, v172
	v_lshlrev_b32_e32 v208, 16, v165
	s_waitcnt vmcnt(5)
; DI float bflo(unsigned u) { return __uint_as_float(u << 16); }
; DI float bfhi(unsigned u) { return __uint_as_float(u & 0xffff0000u); }
;     ...
;             y[j][4 * gq + 0] = bflo(a.x) + bflo(b.x); y[j][4 * gq + 1] = bfhi(a.x) + bfhi(b.x);
;             y[j][4 * gq + 2] = bflo(a.y) + bflo(b.y); y[j][4 * gq + 3] = bfhi(a.y) + bfhi(b.y);
;             sum += y[j][4 * gq] + y[j][4 * gq + 1] + y[j][4 * gq + 2] + y[j][4 * gq + 3];
;           }
;         sum += __shfl_xor(sum, 32);
;         const float mu = sum * (1.f / 64.f);
;         float vs = 0.f;
; #pragma unroll
;         for (int j = 0; j < 2; ++j)
; #pragma unroll
;           for (int r = 0; r < 16; ++r) { float dlt = y[j][r] - mu; vs += dlt * dlt; }
;         vs += __shfl_xor(vs, 32);
;         const float rstd = rsqrtf(vs * (1.f / 64.f) + LNX_EPS);
	v_lshlrev_b32_e32 v231, 16, v176
	v_lshlrev_b32_e32 v230, 16, v163
	v_and_b32_e32 v164, 0xffff0000, v165
	v_lshlrev_b32_e32 v165, 16, v173
	v_and_b32_e32 v162, 0xffff0000, v163
	v_lshlrev_b32_e32 v163, 16, v177
	v_pk_add_f32 v[146:147], v[146:147], v[148:149]
	v_pk_add_f32 v[206:207], v[204:205], v[206:207]
	v_pk_add_f32 v[208:209], v[208:209], v[230:231]
	v_and_b32_e32 v231, 0xffff0000, v172
	v_pk_add_f32 v[162:163], v[164:165], v[162:163]
	v_and_b32_e32 v0, 0xffff0000, v173
	v_lshlrev_b32_e32 v165, 16, v170
	v_lshlrev_b32_e32 v164, 16, v169
	v_lshlrev_b32_e32 v173, 16, v174
	v_lshlrev_b32_e32 v172, 16, v167
	v_pk_mov_b32 v[148:149], v[202:203], v[146:147] op_sel:[1,0]
	v_lshlrev_b32_e32 v226, 16, v168
	v_and_b32_e32 v227, 0xffff0000, v168
	v_pk_add_f32 v[164:165], v[164:165], v[172:173]
	v_and_b32_e32 v173, 0xffff0000, v170
	v_and_b32_e32 v168, 0xffff0000, v169
	v_lshlrev_b32_e32 v169, 16, v171
	v_and_b32_e32 v172, 0xffff0000, v171
	v_pk_add_f32 v[148:149], v[148:149], v[206:207]
	v_mov_b32_e32 v170, v1
	v_mov_b32_e32 v171, v147
	v_pk_add_f32 v[148:149], v[148:149], v[170:171]
	v_and_b32_e32 v219, 0xffff0000, v177
	v_pk_add_f32 v[148:149], v[148:149], v[148:149] op_sel:[0,1] op_sel_hi:[1,0]
	v_and_b32_e32 v233, 0xffff0000, v176
	v_mov_b32_e32 v149, v0
	v_pk_add_f32 v[170:171], v[148:149], v[218:219]
	v_pk_add_f32 v[148:149], v[152:153], v[150:151]
	v_lshlrev_b32_e32 v224, 16, v166
	v_mov_b32_e32 v230, v148
	v_mov_b32_e32 v232, v149
	v_pk_add_f32 v[206:207], v[230:231], v[232:233]
	v_and_b32_e32 v225, 0xffff0000, v166
	v_pk_add_f32 v[150:151], v[208:209], v[206:207]
	v_pk_add_f32 v[152:153], v[226:227], v[224:225]
	v_pk_add_f32 v[150:151], v[150:151], v[162:163]
	v_and_b32_e32 v177, 0xffff0000, v174
	v_pk_add_f32 v[150:151], v[170:171], v[150:151]
	v_mov_b32_e32 v176, v153
	v_pk_add_f32 v[150:151], v[150:151], v[150:151] op_sel:[0,1] op_sel_hi:[1,0]
	v_and_b32_e32 v166, 0xffff0000, v167
	v_mov_b32_e32 v151, v172
	v_mov_b32_e32 v172, v152
	v_lshlrev_b32_e32 v167, 16, v175
	v_pk_add_f32 v[172:173], v[172:173], v[176:177]
	v_pk_add_f32 v[166:167], v[168:169], v[166:167]
	v_and_b32_e32 v221, 0xffff0000, v175
	v_pk_add_f32 v[176:177], v[164:165], v[172:173]
	v_pk_add_f32 v[150:151], v[150:151], v[220:221]
	v_pk_add_f32 v[176:177], v[176:177], v[166:167]
	v_mov_b32_e32 v218, v151
	v_pk_add_f32 v[150:151], v[150:151], v[176:177]
	v_pk_mov_b32 v[174:175], v[204:205], v[228:229] op_sel:[1,0]
	v_add_f32_e32 v0, v150, v151
	ds_bpermute_b32 v150, v137, v0
	v_mov_b32_e32 v205, v162
	v_mov_b32_e32 v170, v163
	v_mov_b32_e32 v168, v166
	v_mov_b32_e32 v169, v164
	s_waitcnt lgkmcnt(0)
	v_add_f32_e32 v0, v0, v150
	v_mul_f32_e32 v0, 0x3c800000, v0
	v_pk_add_f32 v[162:163], v[200:201], v[0:1] op_sel_hi:[1,0] neg_lo:[0,1] neg_hi:[0,1]
	v_mov_b32_e32 v204, v208
	v_mov_b32_e32 v219, v167
	v_mov_b32_e32 v206, v209
	v_mov_b32_e32 v164, v173
	v_pk_mul_f32 v[166:167], v[162:163], v[162:163]
	v_pk_add_f32 v[172:173], v[202:203], v[0:1] op_sel_hi:[1,0] neg_lo:[0,1] neg_hi:[0,1]
	v_pk_add_f32 v[200:201], v[146:147], v[0:1] op_sel_hi:[1,0] neg_lo:[0,1] neg_hi:[0,1]
	v_pk_mul_f32 v[176:177], v[172:173], v[172:173]
	v_pk_add_f32 v[208:209], v[148:149], v[0:1] op_sel_hi:[1,0] neg_lo:[0,1] neg_hi:[0,1]
	v_pk_add_f32 v[152:153], v[152:153], v[0:1] op_sel_hi:[1,0] neg_lo:[0,1] neg_hi:[0,1]
	v_pk_add_f32 v[150:151], v[168:169], v[0:1] op_sel_hi:[1,0] neg_lo:[0,1] neg_hi:[0,1]
	v_pk_add_f32 v[148:149], v[164:165], v[0:1] op_sel_hi:[1,0] neg_lo:[0,1] neg_hi:[0,1]
	v_pk_add_f32 v[146:147], v[218:219], v[0:1] op_sel_hi:[1,0] neg_lo:[0,1] neg_hi:[0,1]
	v_pk_add_f32 v[174:175], v[174:175], v[0:1] op_sel_hi:[1,0] neg_lo:[0,1] neg_hi:[0,1]
	v_pk_add_f32 v[212:213], v[212:213], v[0:1] op_sel_hi:[1,0] neg_lo:[0,1] neg_hi:[0,1]
	v_pk_add_f32 v[210:211], v[210:211], v[0:1] op_sel_hi:[1,0] neg_lo:[0,1] neg_hi:[0,1]
	v_pk_add_f32 v[204:205], v[204:205], v[0:1] op_sel_hi:[1,0] neg_lo:[0,1] neg_hi:[0,1]
	v_pk_add_f32 v[170:171], v[170:171], v[0:1] op_sel_hi:[1,0] neg_lo:[0,1] neg_hi:[0,1]
	v_pk_add_f32 v[206:207], v[206:207], v[0:1] op_sel_hi:[1,0] neg_lo:[0,1] neg_hi:[0,1]
	v_pk_add_f32 v[216:217], v[216:217], v[0:1] op_sel_hi:[1,0] neg_lo:[0,1] neg_hi:[0,1]
	v_pk_add_f32 v[214:215], v[214:215], v[0:1] op_sel_hi:[1,0] neg_lo:[0,1] neg_hi:[0,1]
	v_add_f32_e32 v0, v166, v167
	v_add_f32_e32 v0, v176, v0
	v_pk_mul_f32 v[226:227], v[174:175], v[174:175]
	v_add_f32_e32 v0, v177, v0
	v_add_f32_e32 v0, v226, v0
	v_pk_mul_f32 v[202:203], v[200:201], v[200:201]
	v_add_f32_e32 v0, v227, v0
	v_add_f32_e32 v0, v202, v0
	v_pk_mul_f32 v[230:231], v[210:211], v[210:211]
	v_add_f32_e32 v0, v203, v0
	v_add_f32_e32 v0, v230, v0
	v_pk_mul_f32 v[228:229], v[212:213], v[212:213]
	v_add_f32_e32 v0, v231, v0
	v_add_f32_e32 v0, v229, v0
	v_pk_mul_f32 v[220:221], v[208:209], v[208:209]
	v_add_f32_e32 v0, v228, v0
	v_add_f32_e32 v0, v220, v0
	v_pk_mul_f32 v[232:233], v[204:205], v[204:205]
	v_add_f32_e32 v0, v221, v0
	v_add_f32_e32 v0, v232, v0
	v_pk_mul_f32 v[240:241], v[206:207], v[206:207]
	v_add_f32_e32 v0, v233, v0
	v_add_f32_e32 v0, v240, v0
	v_pk_mul_f32 v[234:235], v[170:171], v[170:171]
	v_add_f32_e32 v0, v241, v0
	v_add_f32_e32 v0, v234, v0
	v_pk_mul_f32 v[244:245], v[214:215], v[214:215]
	v_add_f32_e32 v0, v235, v0
	v_add_f32_e32 v0, v244, v0
	v_pk_mul_f32 v[242:243], v[216:217], v[216:217]
	v_add_f32_e32 v0, v245, v0
	v_add_f32_e32 v0, v243, v0
	v_pk_mul_f32 v[224:225], v[152:153], v[152:153]
	v_add_f32_e32 v0, v242, v0
	v_add_f32_e32 v0, v224, v0
	v_pk_mul_f32 v[168:169], v[150:151], v[150:151]
	v_add_f32_e32 v0, v225, v0
	v_add_f32_e32 v0, v169, v0
	v_pk_mul_f32 v[164:165], v[148:149], v[148:149]
	v_add_f32_e32 v0, v168, v0
	v_add_f32_e32 v0, v165, v0
	v_pk_mul_f32 v[218:219], v[146:147], v[146:147]
	v_add_f32_e32 v0, v164, v0
	v_add_f32_e32 v0, v219, v0
	v_add_f32_e32 v165, v218, v0
	ds_bpermute_b32 v137, v137, v165
	s_waitcnt vmcnt(3)
; DI float bflo(unsigned u) { return __uint_as_float(u << 16); }
; DI float bfhi(unsigned u) { return __uint_as_float(u & 0xffff0000u); }
; DI void store4(u16* dst, float a, float b, float c, float d) { *(uint2*)dst = make_uint2(pack2(a, b), pack2(c, d)); }
;     ...
;         const float rstd = rsqrtf(vs * (1.f / 64.f) + LNX_EPS);
;         const float bsum = p.bsc[(size_t)m * 8 + hd] + p.bsc[((size_t)TP + m) * 8 + hd];
;         const u16* vb = p.regB + (size_t)m * 1952 + 1024;
; #pragma unroll
;         for (int j = 0; j < 2; ++j)
; #pragma unroll
;           for (int gq = 0; gq < 4; ++gq) {
;             int n = nw + j * 32 + 8 * gq + 4 * hh;
;             uint2 c = *(const uint2*)(vb + n);
;             float cv[4] = {bflo(c.x), bfhi(c.x), bflo(c.y), bfhi(c.y)};
;             float o[4];
; #pragma unroll
;             for (int r = 0; r < 4; ++r) {
;               float vsh = cv[r];
;               float yn = (y[j][4 * gq + r] - mu) * rstd * p.lnx_w[g.layer * 512 + n + r] + p.lnx_b[g.layer * 512 + n + r];
;               o[r] = (yn + bsum * vsh) * acc[i][j][4 * gq + r];
;             }
;             store4(yb + n, o[0], o[1], o[2], o[3]);
;           }
	v_add_f32_e32 v0, v178, v199
	s_waitcnt vmcnt(2)
	v_lshlrev_b32_e32 v164, 16, v222
	v_lshlrev_b32_e32 v166, 16, v223
	v_and_b32_e32 v167, 0xffff0000, v223
	s_waitcnt lgkmcnt(0)
	v_add_f32_e32 v137, v165, v137
	v_fmamk_f32 v137, v137, 0x3c800000, v181
	v_mul_f32_e32 v165, 0x4b800000, v137
	v_cmp_gt_f32_e32 vcc, s47, v137
	s_nop 1
	v_cndmask_b32_e32 v137, v137, v165, vcc
	v_rsq_f32_e32 v137, v137
	v_and_b32_e32 v165, 0xffff0000, v222
	v_mul_f32_e32 v168, 0x45800000, v137
	v_cndmask_b32_e32 v168, v137, v168, vcc
	v_pk_mul_f32 v[162:163], v[162:163], v[168:169] op_sel_hi:[1,0]
	s_waitcnt vmcnt(0)
	v_pk_fma_f32 v[154:155], v[154:155], v[162:163], v[158:159]
	v_pk_mul_f32 v[162:163], v[174:175], v[168:169] op_sel_hi:[1,0]
	v_pk_fma_f32 v[154:155], v[0:1], v[164:165], v[154:155] op_sel_hi:[0,1,1]
	v_pk_mul_f32 v[114:115], v[114:115], v[154:155]
	v_pk_mul_f32 v[154:155], v[172:173], v[168:169] op_sel_hi:[1,0]
	v_cvt_pk_bf16_f32 v114, v114, v115
	v_pk_fma_f32 v[154:155], v[156:157], v[154:155], v[160:161]
	s_nop 0
	v_pk_fma_f32 v[154:155], v[0:1], v[166:167], v[154:155] op_sel_hi:[0,1,1]
	v_pk_mul_f32 v[116:117], v[116:117], v[154:155]
	s_nop 0
	v_cvt_pk_bf16_f32 v115, v116, v117
	global_store_dwordx2 v[138:139], v[114:115], off
	global_load_dwordx2 v[158:159], v[144:145], off offset:2064
	s_nop 0
	global_load_dwordx4 v[114:117], v[142:143], off offset:32
	global_load_dwordx4 v[154:157], v[140:141], off offset:32
	s_waitcnt vmcnt(2)
	v_lshlrev_b32_e32 v160, 16, v158
	v_and_b32_e32 v161, 0xffff0000, v158
	s_waitcnt vmcnt(0)
	v_pk_fma_f32 v[114:115], v[114:115], v[162:163], v[154:155]
	v_lshlrev_b32_e32 v158, 16, v159
	v_pk_fma_f32 v[114:115], v[0:1], v[160:161], v[114:115] op_sel_hi:[0,1,1]
	v_pk_mul_f32 v[114:115], v[118:119], v[114:115]
	v_pk_mul_f32 v[118:119], v[200:201], v[168:169] op_sel_hi:[1,0]
	v_and_b32_e32 v159, 0xffff0000, v159
	v_pk_fma_f32 v[116:117], v[116:117], v[118:119], v[156:157]
	v_cvt_pk_bf16_f32 v114, v114, v115
	v_pk_fma_f32 v[116:117], v[0:1], v[158:159], v[116:117] op_sel_hi:[0,1,1]
	v_pk_mul_f32 v[116:117], v[120:121], v[116:117]
	v_pk_mul_f32 v[156:157], v[210:211], v[168:169] op_sel_hi:[1,0]
	v_cvt_pk_bf16_f32 v115, v116, v117
	global_store_dwordx2 v[138:139], v[114:115], off offset:16
	global_load_dwordx2 v[154:155], v[144:145], off offset:2080
	s_nop 0
	global_load_dwordx4 v[114:117], v[142:143], off offset:64
	global_load_dwordx4 v[118:121], v[140:141], off offset:64
	v_pk_mul_f32 v[158:159], v[212:213], v[168:169] op_sel_hi:[1,0]
	s_waitcnt vmcnt(2)
	v_lshlrev_b32_e32 v160, 16, v154
	v_and_b32_e32 v161, 0xffff0000, v154
	v_lshlrev_b32_e32 v154, 16, v155
	v_and_b32_e32 v155, 0xffff0000, v155
	s_waitcnt vmcnt(0)
	v_pk_fma_f32 v[114:115], v[114:115], v[156:157], v[118:119]
	v_pk_fma_f32 v[116:117], v[116:117], v[158:159], v[120:121] op_sel:[0,1,0] op_sel_hi:[1,0,1]
	v_pk_fma_f32 v[114:115], v[0:1], v[160:161], v[114:115] op_sel_hi:[0,1,1]
	v_pk_fma_f32 v[116:117], v[0:1], v[154:155], v[116:117] op_sel_hi:[0,1,1]
	v_pk_mul_f32 v[114:115], v[122:123], v[114:115]
	v_pk_mul_f32 v[116:117], v[124:125], v[116:117]
	v_cvt_pk_bf16_f32 v114, v114, v115
	v_cvt_pk_bf16_f32 v115, v116, v117
	global_store_dwordx2 v[138:139], v[114:115], off offset:32
	global_load_dwordx2 v[122:123], v[144:145], off offset:2096
	s_nop 0
	global_load_dwordx4 v[114:117], v[142:143], off offset:96
	global_load_dwordx4 v[118:121], v[140:141], off offset:96
	v_pk_mul_f32 v[124:125], v[208:209], v[168:169] op_sel_hi:[1,0]
	v_pk_mul_f32 v[154:155], v[204:205], v[168:169] op_sel_hi:[1,0]
	s_waitcnt vmcnt(2)
	v_lshlrev_b32_e32 v156, 16, v122
	v_and_b32_e32 v157, 0xffff0000, v122
	v_lshlrev_b32_e32 v122, 16, v123
	v_and_b32_e32 v123, 0xffff0000, v123
	s_waitcnt vmcnt(0)
	v_pk_fma_f32 v[114:115], v[114:115], v[124:125], v[118:119]
	v_pk_fma_f32 v[116:117], v[116:117], v[154:155], v[120:121]
	v_pk_fma_f32 v[114:115], v[0:1], v[156:157], v[114:115] op_sel_hi:[0,1,1]
	v_pk_fma_f32 v[116:117], v[0:1], v[122:123], v[116:117] op_sel_hi:[0,1,1]
	v_pk_mul_f32 v[114:115], v[126:127], v[114:115]
	v_pk_mul_f32 v[116:117], v[128:129], v[116:117]
	v_cvt_pk_bf16_f32 v114, v114, v115
	v_cvt_pk_bf16_f32 v115, v116, v117
	global_store_dwordx2 v[138:139], v[114:115], off offset:48
	global_load_dwordx2 v[122:123], v[144:145], off offset:2112
	s_nop 0
	global_load_dwordx4 v[114:117], v[142:143], off offset:128
	global_load_dwordx4 v[118:121], v[140:141], off offset:128
	v_pk_mul_f32 v[124:125], v[206:207], v[168:169] op_sel_hi:[1,0]
	v_pk_mul_f32 v[126:127], v[170:171], v[168:169] op_sel_hi:[1,0]
	s_waitcnt vmcnt(2)
; DI float bflo(unsigned u) { return __uint_as_float(u << 16); }
; DI float bfhi(unsigned u) { return __uint_as_float(u & 0xffff0000u); }
; DI void store4(u16* dst, float a, float b, float c, float d) { *(uint2*)dst = make_uint2(pack2(a, b), pack2(c, d)); }
;     ...
; #pragma unroll
;         for (int j = 0; j < 2; ++j)
; #pragma unroll
;           for (int gq = 0; gq < 4; ++gq) {
;             int n = nw + j * 32 + 8 * gq + 4 * hh;
;             uint2 c = *(const uint2*)(vb + n);
;             float cv[4] = {bflo(c.x), bfhi(c.x), bflo(c.y), bfhi(c.y)};
;             float o[4];
; #pragma unroll
;             for (int r = 0; r < 4; ++r) {
;               float vsh = cv[r];
;               float yn = (y[j][4 * gq + r] - mu) * rstd * p.lnx_w[g.layer * 512 + n + r] + p.lnx_b[g.layer * 512 + n + r];
;               o[r] = (yn + bsum * vsh) * acc[i][j][4 * gq + r];
;             }
;             store4(yb + n, o[0], o[1], o[2], o[3]);
;           }
	v_lshlrev_b32_e32 v128, 16, v122
	v_and_b32_e32 v129, 0xffff0000, v122
	v_lshlrev_b32_e32 v122, 16, v123
	v_and_b32_e32 v123, 0xffff0000, v123
	s_waitcnt vmcnt(0)
	v_pk_fma_f32 v[114:115], v[124:125], v[114:115], v[118:119]
	v_pk_fma_f32 v[116:117], v[126:127], v[116:117], v[120:121]
	v_pk_fma_f32 v[114:115], v[0:1], v[128:129], v[114:115] op_sel_hi:[0,1,1]
	v_pk_fma_f32 v[116:117], v[0:1], v[122:123], v[116:117] op_sel_hi:[0,1,1]
	v_pk_mul_f32 v[98:99], v[98:99], v[114:115]
	v_pk_mul_f32 v[100:101], v[100:101], v[116:117]
	v_cvt_pk_bf16_f32 v98, v98, v99
	v_cvt_pk_bf16_f32 v99, v100, v101
	global_store_dwordx2 v[138:139], v[98:99], off offset:64
	global_load_dwordx2 v[118:119], v[144:145], off offset:2128
	s_nop 0
	global_load_dwordx4 v[98:101], v[142:143], off offset:160
	global_load_dwordx4 v[114:117], v[140:141], off offset:160
	v_pk_mul_f32 v[120:121], v[214:215], v[168:169] op_sel_hi:[1,0]
	v_pk_mul_f32 v[122:123], v[216:217], v[168:169] op_sel_hi:[1,0]
	s_waitcnt vmcnt(2)
	v_lshlrev_b32_e32 v124, 16, v118
	v_and_b32_e32 v125, 0xffff0000, v118
	v_lshlrev_b32_e32 v118, 16, v119
	v_and_b32_e32 v119, 0xffff0000, v119
	s_waitcnt vmcnt(0)
	v_pk_fma_f32 v[98:99], v[120:121], v[98:99], v[114:115]
	v_pk_fma_f32 v[100:101], v[122:123], v[100:101], v[116:117] op_sel:[1,0,0] op_sel_hi:[0,1,1]
	v_pk_fma_f32 v[98:99], v[0:1], v[124:125], v[98:99] op_sel_hi:[0,1,1]
	v_pk_fma_f32 v[100:101], v[0:1], v[118:119], v[100:101] op_sel_hi:[0,1,1]
	v_pk_mul_f32 v[98:99], v[102:103], v[98:99]
	v_pk_mul_f32 v[100:101], v[104:105], v[100:101]
	v_cvt_pk_bf16_f32 v98, v98, v99
	v_cvt_pk_bf16_f32 v99, v100, v101
	global_store_dwordx2 v[138:139], v[98:99], off offset:80
	global_load_dwordx2 v[114:115], v[144:145], off offset:2144
	s_nop 0
	global_load_dwordx4 v[98:101], v[142:143], off offset:192
	global_load_dwordx4 v[102:105], v[140:141], off offset:192
	v_pk_mul_f32 v[116:117], v[152:153], v[168:169] op_sel_hi:[1,0]
	v_pk_mul_f32 v[118:119], v[150:151], v[168:169] op_sel_hi:[1,0]
	s_waitcnt vmcnt(2)
	v_lshlrev_b32_e32 v120, 16, v114
	v_and_b32_e32 v121, 0xffff0000, v114
	v_lshlrev_b32_e32 v114, 16, v115
	v_and_b32_e32 v115, 0xffff0000, v115
	s_waitcnt vmcnt(0)
	v_pk_fma_f32 v[98:99], v[116:117], v[98:99], v[102:103]
	v_pk_fma_f32 v[100:101], v[118:119], v[100:101], v[104:105] op_sel:[1,0,0] op_sel_hi:[0,1,1]
	v_pk_fma_f32 v[98:99], v[0:1], v[120:121], v[98:99] op_sel_hi:[0,1,1]
	v_pk_fma_f32 v[100:101], v[0:1], v[114:115], v[100:101] op_sel_hi:[0,1,1]
	v_pk_mul_f32 v[98:99], v[106:107], v[98:99]
	v_pk_mul_f32 v[100:101], v[108:109], v[100:101]
	v_cvt_pk_bf16_f32 v98, v98, v99
	v_cvt_pk_bf16_f32 v99, v100, v101
	global_store_dwordx2 v[138:139], v[98:99], off offset:96
	global_load_dwordx2 v[106:107], v[144:145], off offset:2160
	s_nop 0
	global_load_dwordx4 v[98:101], v[142:143], off offset:224
	global_load_dwordx4 v[102:105], v[140:141], off offset:224
	v_pk_mul_f32 v[108:109], v[148:149], v[168:169] op_sel_hi:[1,0]
	v_pk_mul_f32 v[114:115], v[146:147], v[168:169] op_sel_hi:[1,0]
	s_waitcnt vmcnt(2)
	v_lshlrev_b32_e32 v116, 16, v106
	v_and_b32_e32 v117, 0xffff0000, v106
	v_lshlrev_b32_e32 v106, 16, v107
	v_and_b32_e32 v107, 0xffff0000, v107
	s_waitcnt vmcnt(0)
	v_pk_fma_f32 v[98:99], v[108:109], v[98:99], v[102:103] op_sel:[1,0,0] op_sel_hi:[0,1,1]
	v_pk_fma_f32 v[100:101], v[114:115], v[100:101], v[104:105] op_sel:[1,0,0] op_sel_hi:[0,1,1]
	v_pk_fma_f32 v[98:99], v[0:1], v[116:117], v[98:99] op_sel_hi:[0,1,1]
	v_pk_fma_f32 v[100:101], v[0:1], v[106:107], v[100:101] op_sel_hi:[0,1,1]
	v_pk_mul_f32 v[98:99], v[110:111], v[98:99]
	v_pk_mul_f32 v[100:101], v[112:113], v[100:101]
	v_cvt_pk_bf16_f32 v98, v98, v99
	v_cvt_pk_bf16_f32 v99, v100, v101
	global_store_dwordx2 v[138:139], v[98:99], off offset:112

;     ...
;     auto compute2 = [&](int buf) {
;       const char* lb = L0 + buf * BUFB;
; #pragma unroll
;       for (int ks = 0; ks < 4; ++ks) {
;         const int c = ks * 2 + hh;
;         bf16x8 wf[2], xf[MI];
; #pragma unroll
;         for (int j = 0; j < 2; ++j) { const int r = wn * 64 + j * 32 + l32; wf[j] = *(const bf16x8*)(lb + 256 * 128 + r * 128 + ((c ^ ((r >> 1) & 7)) << 4)); }
; #pragma unroll
;         for (int i = 0; i < MI; ++i) { const int r = wm * (MI * 32) + i * 32 + l32; xf[i] = *(const bf16x8*)(lb + r * 128 + ((c ^ ((r >> 1) & 7)) << 4)); }
; #pragma unroll
;         for (int i = 0; i < MI; ++i) {
;           acc[i][0] = MFMA(wf[0], xf[i], acc[i][0]);
;           acc[i][1] = MFMA(wf[1], xf[i], acc[i][1]);
;         }
;       }
;     };
;     ...
;     } else if (EPI == EPI_INPROJ) {
;       const float rs = rsl[m - m0];
;       int s, pos, L; row2seq(m < T ? m : 0, s, pos, L);
;       float ss = 0.f;
; #pragma unroll
;       for (int j = 0; j < 2; ++j) {
;         const int nb = nw + j * 32;
;         if (nb == 384) {
;           u16* kr = (u16*)p.out + (size_t)TP * 1024 + (size_t)TP * 768 + (size_t)m * 32;
; #pragma unroll
;           for (int gq = 0; gq < 2; ++gq) {
;             float o1[4], o2[4];
; #pragma unroll
;             for (int r = 0; r < 4; ++r) {
;               int ii = 8 * gq + 4 * hh + r;
;               float c = p.ropec[pos * 16 + ii], sn = p.ropes[pos * 16 + ii];
;               float x1 = acc[i][j][4 * gq + r] * rs, x2 = acc[i][j][4 * (gq + 2) + r] * rs;
;               o1[r] = x1 * c - x2 * sn; o2[r] = x2 * c + x1 * sn;
;             }
;             store4(kr + 8 * gq + 4 * hh, o1[0], o1[1], o1[2], o1[3]);
;             store4(kr + 16 + 8 * gq + 4 * hh, o2[0], o2[1], o2[2], o2[3]);
;           }
;         } else {
; #pragma unroll
;           for (int gq = 0; gq < 4; ++gq) {
;             int n = nb + 8 * gq + 4 * hh;
;             unsigned p0 = pack2(acc[i][j][4 * gq] * rs, acc[i][j][4 * gq + 1] * rs);
;             unsigned p1 = pack2(acc[i][j][4 * gq + 2] * rs, acc[i][j][4 * gq + 3] * rs);
;             if (n < 512) {
;               *(uint2*)((u16*)p.out + (size_t)m * 512 + n) = make_uint2(p0, p1);
;               float r0 = bflo(p0), r1 = bfhi(p0), r2 = bflo(p1), r3 = bfhi(p1);
;               ss += r0 * r0 + r1 * r1 + r2 * r2 + r3 * r3;
;             } else if (n - 512 < 1952) {
.LBB0_801:
	v_add3_u32 v0, s25, v175, v171
	ds_read_b128 v[130:133], v0
	ds_read_b128 v[138:141], v0 offset:4096
	v_add3_u32 v142, s24, v175, v170
	ds_read_b128 v[134:137], v142
	v_add3_u32 v0, s25, v174, v171
	s_waitcnt lgkmcnt(0)
	v_mfma_f32_32x32x16_bf16 v[114:129], v[130:133], v[134:137], v[114:129]
	v_mfma_f32_32x32x16_bf16 v[98:113], v[138:141], v[134:137], v[98:113]
	ds_read_b128 v[134:137], v142 offset:4096
	s_waitcnt lgkmcnt(0)
	v_mfma_f32_32x32x16_bf16 v[82:97], v[130:133], v[134:137], v[82:97]
	v_mfma_f32_32x32x16_bf16 v[66:81], v[138:141], v[134:137], v[66:81]
	ds_read_b128 v[134:137], v142 offset:8192
	s_waitcnt lgkmcnt(0)
	v_mfma_f32_32x32x16_bf16 v[50:65], v[130:133], v[134:137], v[50:65]
	v_mfma_f32_32x32x16_bf16 v[34:49], v[138:141], v[134:137], v[34:49]
	ds_read_b128 v[134:137], v142 offset:12288
	v_add3_u32 v142, s24, v174, v170
	s_waitcnt lgkmcnt(0)
	v_mfma_f32_32x32x16_bf16 v[18:33], v[130:133], v[134:137], v[18:33]
	ds_read_b128 v[130:133], v0
	v_mfma_f32_32x32x16_bf16 v[2:17], v[138:141], v[134:137], v[2:17]
	ds_read_b128 v[138:141], v0 offset:4096
	ds_read_b128 v[134:137], v142
	v_add3_u32 v0, s25, v173, v171
	s_waitcnt lgkmcnt(0)
	v_mfma_f32_32x32x16_bf16 v[114:129], v[130:133], v[134:137], v[114:129]
	v_mfma_f32_32x32x16_bf16 v[98:113], v[138:141], v[134:137], v[98:113]
	ds_read_b128 v[134:137], v142 offset:4096
	s_waitcnt lgkmcnt(0)
	v_mfma_f32_32x32x16_bf16 v[82:97], v[130:133], v[134:137], v[82:97]
	v_mfma_f32_32x32x16_bf16 v[66:81], v[138:141], v[134:137], v[66:81]
	ds_read_b128 v[134:137], v142 offset:8192
	s_waitcnt lgkmcnt(0)
	v_mfma_f32_32x32x16_bf16 v[50:65], v[130:133], v[134:137], v[50:65]
	v_mfma_f32_32x32x16_bf16 v[34:49], v[138:141], v[134:137], v[34:49]
	ds_read_b128 v[134:137], v142 offset:12288
	v_add3_u32 v142, s24, v173, v170
	s_waitcnt lgkmcnt(0)
	v_mfma_f32_32x32x16_bf16 v[18:33], v[130:133], v[134:137], v[18:33]
	ds_read_b128 v[130:133], v0
	v_mfma_f32_32x32x16_bf16 v[2:17], v[138:141], v[134:137], v[2:17]
	ds_read_b128 v[138:141], v0 offset:4096
	ds_read_b128 v[134:137], v142
	v_add3_u32 v0, s25, v172, v171
	s_waitcnt lgkmcnt(0)
	v_mfma_f32_32x32x16_bf16 v[114:129], v[130:133], v[134:137], v[114:129]
	v_mfma_f32_32x32x16_bf16 v[98:113], v[138:141], v[134:137], v[98:113]
	ds_read_b128 v[134:137], v142 offset:4096
	s_waitcnt lgkmcnt(0)
	v_mfma_f32_32x32x16_bf16 v[82:97], v[130:133], v[134:137], v[82:97]
	v_mfma_f32_32x32x16_bf16 v[66:81], v[138:141], v[134:137], v[66:81]
	ds_read_b128 v[134:137], v142 offset:8192
	s_waitcnt lgkmcnt(0)
	v_mfma_f32_32x32x16_bf16 v[50:65], v[130:133], v[134:137], v[50:65]
	v_mfma_f32_32x32x16_bf16 v[34:49], v[138:141], v[134:137], v[34:49]
	ds_read_b128 v[134:137], v142 offset:12288
	v_add3_u32 v142, s24, v172, v170
	s_waitcnt lgkmcnt(0)
	v_mfma_f32_32x32x16_bf16 v[18:33], v[130:133], v[134:137], v[18:33]
	ds_read_b128 v[130:133], v0
	v_mfma_f32_32x32x16_bf16 v[2:17], v[138:141], v[134:137], v[2:17]
	ds_read_b128 v[138:141], v0 offset:4096
	ds_read_b128 v[134:137], v142
	s_waitcnt lgkmcnt(0)
	v_mfma_f32_32x32x16_bf16 v[114:129], v[130:133], v[134:137], v[114:129]
	v_mfma_f32_32x32x16_bf16 v[98:113], v[138:141], v[134:137], v[98:113]
	ds_read_b128 v[134:137], v142 offset:4096
	s_waitcnt lgkmcnt(0)
	v_mfma_f32_32x32x16_bf16 v[82:97], v[130:133], v[134:137], v[82:97]
	v_mfma_f32_32x32x16_bf16 v[66:81], v[138:141], v[134:137], v[66:81]
	ds_read_b128 v[134:137], v142 offset:8192
	s_waitcnt lgkmcnt(0)
	v_mfma_f32_32x32x16_bf16 v[50:65], v[130:133], v[134:137], v[50:65]
	v_mfma_f32_32x32x16_bf16 v[34:49], v[138:141], v[134:137], v[34:49]
	ds_read_b128 v[134:137], v142 offset:12288
	s_waitcnt vmcnt(0)
	s_waitcnt vmcnt(0) lgkmcnt(0)
	s_barrier
	v_mfma_f32_32x32x16_bf16 v[18:33], v[130:133], v[134:137], v[18:33]
	v_mfma_f32_32x32x16_bf16 v[2:17], v[138:141], v[134:137], v[2:17]
	s_and_saveexec_b64 s[2:3], s[40:41]
	v_lshl_add_u32 v0, v155, 2, 0
	v_add_u32_e32 v0, 0x24000, v0
	ds_write_b32 v0, v156
	s_or_b64 exec, exec, s[2:3]
	v_lshl_add_u32 v0, v163, 7, s60
	v_or_b32_e32 v130, v0, v164
	v_subrev_u32_e32 v0, s60, v130
	v_lshl_add_u32 v0, v0, 2, 0
	v_add_u32_e32 v0, 0x24000, v0
	s_waitcnt lgkmcnt(0)
	s_barrier
	ds_read_b32 v138, v0
	s_mov_b32 s2, 0x80a0
	v_cmp_gt_i32_e32 vcc, s2, v130
	s_movk_i32 s2, 0x401f
	s_nop 0
	v_cndmask_b32_e32 v0, 0, v130, vcc
	v_cmp_lt_i32_e64 s[40:41], s2, v0
	s_and_saveexec_b64 s[2:3], s[40:41]
	s_xor_b64 s[2:3], exec, s[2:3]
	v_add_u32_e32 v0, 0xffffbfe0, v0
	s_mov_b32 s11, 0xfe03f81
	v_mul_hi_u32 v131, v0, s11
	v_lshrrev_b32_e32 v131, 7, v131
	s_movk_i32 s11, 0xf7f0
	v_add_u32_e32 v134, 2, v131
	v_mad_i32_i24 v133, v131, s11, v0
	s_andn2_saveexec_b64 s[2:3], s[2:3]
	s_movk_i32 s11, 0x200f
	v_cmp_lt_i32_e64 s[40:41], s11, v0
	s_nop 1
	v_cndmask_b32_e64 v131, 0, v195, s[40:41]
	v_cndmask_b32_e64 v134, 0, 1, s[40:41]
	v_add_u32_e32 v133, v131, v0
	s_or_b64 exec, exec, s[2:3]
	v_mov_b64_e32 v[136:137], s[72:73]
	v_ashrrev_i32_e32 v131, 31, v130
	v_mad_i64_i32 v[140:141], s[2:3], v130, s88, v[136:137]
	v_and_b32_e32 v148, 63, v133
	v_lshl_add_u32 v132, v158, 6, s10
	v_lshlrev_b32_e32 v0, 2, v159
	v_cmp_gt_u32_e64 s[44:45], 2, v134
	v_mad_i32_i24 v144, v134, 33, v197
	v_mul_i32_i24_e32 v145, 0x81, v134
	v_cmp_ne_u32_e64 s[40:41], 0, v148
	v_lshlrev_b64 v[134:135], 10, v[130:131]
	s_movk_i32 s2, 0x180
	v_ashrrev_i32_e32 v146, 6, v133
	v_cndmask_b32_e64 v147, 0, 1, s[40:41]
	v_lshl_add_u64 v[142:143], s[78:79], 0, v[134:135]
	v_cmp_ne_u32_e64 s[40:41], s2, v132
	v_or_b32_e32 v134, v132, v0
	s_and_saveexec_b64 s[2:3], s[40:41]
	s_xor_b64 s[2:3], exec, s[2:3]
	s_cbranch_execz .LBB0_849
	s_waitcnt lgkmcnt(0)
	v_pk_mul_f32 v[114:115], v[114:115], v[138:139] op_sel_hi:[1,0]
	v_pk_mul_f32 v[116:117], v[116:117], v[138:139] op_sel_hi:[1,0]
	s_movk_i32 s10, 0x1ff
	v_cvt_pk_bf16_f32 v114, v114, v115
	v_cvt_pk_bf16_f32 v115, v116, v117
	v_cmp_lt_i32_e64 s[42:43], s10, v134
	s_and_saveexec_b64 s[10:11], s[42:43]
	s_xor_b64 s[10:11], exec, s[10:11]
	s_cbranch_execz .LBB0_816
	s_movk_i32 s14, 0x9a0
	v_cmp_gt_u32_e64 s[42:43], s14, v132
	s_and_saveexec_b64 s[14:15], s[42:43]
	s_cbranch_execz .LBB0_815
	v_add_u32_e32 v116, 0xfffffe00, v134
	v_mov_b32_e32 v117, v1
	v_lshl_add_u64 v[136:137], v[116:117], 1, v[140:141]
	global_store_dwordx2 v[136:137], v[114:115], off
	s_and_b64 exec, exec, vcc
	s_cbranch_execz .LBB0_815
	v_cmp_gt_i32_e64 s[42:43], 63, v148
	s_mov_b64 s[16:17], -1
	s_and_saveexec_b64 s[46:47], s[42:43]
	v_cmp_eq_u32_e64 s[42:43], 0, v148
	s_orn2_b64 s[16:17], s[42:43], exec
	s_or_b64 exec, exec, s[46:47]
	s_and_b64 exec, exec, s[16:17]
	s_cbranch_execz .LBB0_815
	v_cndmask_b32_e64 v133, v144, v145, s[44:45]
	v_add_u32_e32 v133, v133, v146
	v_ashrrev_i32_e32 v135, 31, v133
	v_lshl_or_b32 v133, v133, 1, v147
	v_mov_b64_e32 v[136:137], s[74:75]
	v_mad_u64_u32 v[136:137], s[16:17], v133, s88, v[136:137]
	v_mad_i32_i24 v137, v135, s88, v137
	v_lshl_add_u64 v[116:117], v[116:117], 1, v[136:137]
	global_store_dwordx2 v[116:117], v[114:115], off

; #define MFMA(a, b, c) __builtin_amdgcn_mfma_f32_32x32x16_bf16((a), (b), (c), 0, 0, 0)
; #define GLOAD(KT, DA, DW) do { GLA(KT, DA, 0) GLA(KT, DA, 1) GLA(KT, DA, 2) GLA(KT, DA, 3) GLW(KT, DW, 0) GLW(KT, DW, 1) GLW(KT, DW, 2) GLW(KT, DW, 3) } while (0)
; #define LSTORE(BUF, DA, DW) do { LSA(BUF, DA, 0) LSA(BUF, DA, 1) LSA(BUF, DA, 2) LSA(BUF, DA, 3) LSW(BUF, DW, 0) LSW(BUF, DW, 1) LSW(BUF, DW, 2) LSW(BUF, DW, 3) } while (0)
;     ...
;     auto compute2 = [&](int buf) {
;       const char* lb = L0 + buf * BUFB;
; #pragma unroll
;       for (int ks = 0; ks < 4; ++ks) {
;         const int c = ks * 2 + hh;
;         bf16x8 wf[2], xf[MI];
; #pragma unroll
;         for (int j = 0; j < 2; ++j) { const int r = wn * 64 + j * 32 + l32; wf[j] = *(const bf16x8*)(lb + 256 * 128 + r * 128 + ((c ^ ((r >> 1) & 7)) << 4)); }
; #pragma unroll
;         for (int i = 0; i < MI; ++i) { const int r = wm * (MI * 32) + i * 32 + l32; xf[i] = *(const bf16x8*)(lb + r * 128 + ((c ^ ((r >> 1) & 7)) << 4)); }
; #pragma unroll
;         for (int i = 0; i < MI; ++i) {
;           acc[i][0] = MFMA(wf[0], xf[i], acc[i][0]);
;           acc[i][1] = MFMA(wf[1], xf[i], acc[i][1]);
;         }
;       }
;     };
;     ...
;       for (int kt = 0; kt < nk; ++kt) {
;         const int buf = kt & 1;
;         if (kt + 1 < nk) issue(kt + 1, buf ^ 1);
;         else if (chain & 2) issue_at(nmt * 256, nnt * BN, 0, buf ^ 1);
;         compute2(buf);
;         asm volatile("s_waitcnt vmcnt(0)" ::: "memory");
;         __syncthreads();
;       }
;     }
;     __syncthreads();
;   } else {
;     GLOAD(0, ra0, rw0);
;     LSTORE(0, ra0, rw0);
;     __syncthreads();
;     for (int kt = 0; kt < nk; ++kt) {
;       const int buf = kt & 1;
;       if (kt + 1 < nk) GLOAD(kt + 1, ra0, rw0);
;       compute(buf);
;       if (kt + 1 < nk) LSTORE(buf ^ 1, ra0, rw0);
;       __syncthreads();
;     }
;   }
;     ...
;   float* rsl = (float*)(smem + 147456);
;   if (EPI == EPI_UP || EPI == EPI_INPROJ) {
;     if (tid < 256) rsl[tid] = rs_early;
;     __syncthreads();
.LBB0_1374:
	v_add3_u32 v0, s25, v174, v170
	v_add3_u32 v142, s24, v174, v169
	ds_read_b128 v[130:133], v0
	ds_read_b128 v[138:141], v0 offset:4096
	ds_read_b128 v[134:137], v142
	ds_read_b128 v[204:207], v142 offset:4096
	ds_read_b128 v[208:211], v142 offset:8192
	ds_read_b128 v[212:215], v142 offset:12288
	v_add3_u32 v0, s25, v173, v170
	v_add3_u32 v142, s24, v173, v169
	s_waitcnt lgkmcnt(3)
	v_mfma_f32_32x32x16_bf16 v[114:129], v[130:133], v[134:137], v[114:129]
	ds_read_b128 v[216:219], v0
	v_mfma_f32_32x32x16_bf16 v[98:113], v[138:141], v[134:137], v[98:113]
	ds_read_b128 v[220:223], v0 offset:4096
	s_waitcnt lgkmcnt(4)
	v_mfma_f32_32x32x16_bf16 v[82:97], v[130:133], v[204:207], v[82:97]
	ds_read_b128 v[224:227], v142
	v_mfma_f32_32x32x16_bf16 v[66:81], v[138:141], v[204:207], v[66:81]
	ds_read_b128 v[204:207], v142 offset:4096
	s_waitcnt lgkmcnt(5)
	v_mfma_f32_32x32x16_bf16 v[50:65], v[130:133], v[208:211], v[50:65]
	v_mfma_f32_32x32x16_bf16 v[34:49], v[138:141], v[208:211], v[34:49]
	ds_read_b128 v[208:211], v142 offset:8192
	s_waitcnt lgkmcnt(5)
	v_mfma_f32_32x32x16_bf16 v[18:33], v[130:133], v[212:215], v[18:33]
	v_mfma_f32_32x32x16_bf16 v[2:17], v[138:141], v[212:215], v[2:17]
	ds_read_b128 v[212:215], v142 offset:12288
	v_add3_u32 v0, s25, v172, v170
	v_add3_u32 v142, s24, v172, v169
	s_waitcnt lgkmcnt(3)
	v_mfma_f32_32x32x16_bf16 v[114:129], v[216:219], v[224:227], v[114:129]
	ds_read_b128 v[130:133], v0
	v_mfma_f32_32x32x16_bf16 v[98:113], v[220:223], v[224:227], v[98:113]
	ds_read_b128 v[138:141], v0 offset:4096
	s_waitcnt lgkmcnt(4)
	v_mfma_f32_32x32x16_bf16 v[82:97], v[216:219], v[204:207], v[82:97]
	ds_read_b128 v[134:137], v142
	v_mfma_f32_32x32x16_bf16 v[66:81], v[220:223], v[204:207], v[66:81]
	ds_read_b128 v[204:207], v142 offset:4096
	s_waitcnt lgkmcnt(5)
	v_mfma_f32_32x32x16_bf16 v[50:65], v[216:219], v[208:211], v[50:65]
	v_mfma_f32_32x32x16_bf16 v[34:49], v[220:223], v[208:211], v[34:49]
	ds_read_b128 v[208:211], v142 offset:8192
	s_waitcnt lgkmcnt(5)
	v_mfma_f32_32x32x16_bf16 v[18:33], v[216:219], v[212:215], v[18:33]
	v_mfma_f32_32x32x16_bf16 v[2:17], v[220:223], v[212:215], v[2:17]
	ds_read_b128 v[212:215], v142 offset:12288
	v_add3_u32 v0, s25, v171, v170
	v_add3_u32 v142, s24, v171, v169
	s_waitcnt lgkmcnt(3)
	v_mfma_f32_32x32x16_bf16 v[114:129], v[130:133], v[134:137], v[114:129]
	ds_read_b128 v[216:219], v0
	v_mfma_f32_32x32x16_bf16 v[98:113], v[138:141], v[134:137], v[98:113]
	ds_read_b128 v[220:223], v0 offset:4096
	s_waitcnt lgkmcnt(4)
	v_mfma_f32_32x32x16_bf16 v[82:97], v[130:133], v[204:207], v[82:97]
	ds_read_b128 v[224:227], v142
	v_mfma_f32_32x32x16_bf16 v[66:81], v[138:141], v[204:207], v[66:81]
	ds_read_b128 v[204:207], v142 offset:4096
	s_waitcnt lgkmcnt(5)
	v_mfma_f32_32x32x16_bf16 v[50:65], v[130:133], v[208:211], v[50:65]
	v_mfma_f32_32x32x16_bf16 v[34:49], v[138:141], v[208:211], v[34:49]
	ds_read_b128 v[208:211], v142 offset:8192
	s_waitcnt lgkmcnt(5)
	v_mfma_f32_32x32x16_bf16 v[18:33], v[130:133], v[212:215], v[18:33]
	v_mfma_f32_32x32x16_bf16 v[2:17], v[138:141], v[212:215], v[2:17]
	ds_read_b128 v[212:215], v142 offset:12288
	s_waitcnt lgkmcnt(0)
	s_barrier
	v_mfma_f32_32x32x16_bf16 v[114:129], v[216:219], v[224:227], v[114:129]
	v_mfma_f32_32x32x16_bf16 v[98:113], v[220:223], v[224:227], v[98:113]
	v_mfma_f32_32x32x16_bf16 v[82:97], v[216:219], v[204:207], v[82:97]
	v_mfma_f32_32x32x16_bf16 v[66:81], v[220:223], v[204:207], v[66:81]
	v_mfma_f32_32x32x16_bf16 v[50:65], v[216:219], v[208:211], v[50:65]
	v_mfma_f32_32x32x16_bf16 v[34:49], v[220:223], v[208:211], v[34:49]
	v_mfma_f32_32x32x16_bf16 v[18:33], v[216:219], v[212:215], v[18:33]
	v_mfma_f32_32x32x16_bf16 v[2:17], v[220:223], v[212:215], v[2:17]
	s_and_saveexec_b64 s[16:17], s[40:41]
	s_cbranch_execz .LBB0_1363
	v_lshl_add_u32 v0, v154, 2, 0
	v_add_u32_e32 v0, 0x24000, v0
	ds_write_b32 v0, v155
	s_branch .LBB0_1363
